# indexer top-k: hand-written register-resident radix select (scores loaded once into VGPRs, 3 LDS-histogram passes + final pass from registers)
# speedup vs baseline: 1.0410x; 1.0300x over previous
.Lsel_done:
	s_add_i32 s63, s63, s70
	s_cmpk_lt_i32 s63, 0x400
	s_cbranch_scc0 .LBB0_2269

.LBB0_1110:
	s_waitcnt vmcnt(0)
	s_waitcnt vmcnt(0)
	buffer_inv sc1
	s_waitcnt vmcnt(0)
.Lsel_start:
	s_mov_b64 exec, -1
	v_mbcnt_lo_u32_b32 v131, -1, 0
	v_mbcnt_hi_u32_b32 v131, -1, v131
	v_lshlrev_b32_e32 v133, 2, v131
	v_mov_b32_e32 v135, 1
	v_readfirstlane_b32 s16, v146
	s_lshr_b32 s16, s16, 6
	s_lshl_b32 s93, s16, 13
	s_add_i32 s93, s93, 73728
	v_mov_b32_e32 v136, s93
	s_lshl_b32 s93, s16, 8
	s_add_i32 s93, s93, 139264
	v_add_u32_e32 v137, s93, v133
	s_ashr_i32 s17, s63, 9
	s_and_b32 s93, s63, 0x1ff
	s_sub_i32 s94, 0x2ff, s93
	s_cmpk_lt_u32 s93, 0x100
	s_cselect_b32 s93, s93, s94
	s_lshl_b32 s18, s93, 4
	s_mov_b32 s19, 0
.Lsel_q:
	s_mov_b64 exec, -1
	s_lshl_b32 s93, s16, 1
	s_add_i32 s93, s93, s19
	s_add_i32 s22, s18, s93
	s_add_i32 s33, s22, 1
	s_lshl_b32 s94, s2, 4
	s_add_i32 s42, s94, s93
	s_mov_b32 s43, 0
	s_lshl_b64 s[42:43], s[42:43], 15
	s_add_u32 s42, s42, s30
	s_addc_u32 s43, s43, s31
	s_add_u32 s42, s42, 0x1a000000
	s_addc_u32 s43, s43, 0
	s_lshl_b32 s93, s17, 23
	s_lshl_b32 s94, s22, 3
	s_add_i32 s93, s93, s94
	s_add_i32 s93, s93, 0x19000000
	s_add_u32 s50, s30, s93
	s_addc_u32 s51, s31, 0
	s_lshr_b32 s35, s22, 8
	s_add_i32 s35, s35, 1
	s_lshl_b32 s35, s35, 2
	s_add_i32 s34, s33, 63
	s_lshr_b32 s34, s34, 6
	v_sub_u32_e32 v138, s33, v131
	v_mov_b32_e32 v250, 0
	v_mov_b32_e32 v251, 0
	v_mov_b32_e32 v252, 0
	v_mov_b32_e32 v253, 0
	s_cmpk_gt_u32 s33, 0x100
	s_cbranch_scc1 .Lsel_big
	v_cmp_lt_i32_e32 vcc, 0, v138
	s_nop 3
	v_writelane_b32 v250, vcc_lo, 0
	v_writelane_b32 v251, vcc_hi, 0
	v_cmp_lt_i32_e32 vcc, 64, v138
	s_nop 3
	v_writelane_b32 v250, vcc_lo, 1
	v_writelane_b32 v251, vcc_hi, 1
	v_cmp_lt_i32_e32 vcc, 0x80, v138
	s_nop 3
	v_writelane_b32 v250, vcc_lo, 2
	v_writelane_b32 v251, vcc_hi, 2
	v_cmp_lt_i32_e32 vcc, 0xc0, v138
	s_nop 3
	v_writelane_b32 v250, vcc_lo, 3
	v_writelane_b32 v251, vcc_hi, 3
	s_branch .Lsel_store
.Lsel_big:
	s_mov_b64 s[44:45], s[42:43]
	global_load_dword v0, v133, s[44:45]
	global_load_dword v1, v133, s[44:45] offset:256
	global_load_dword v2, v133, s[44:45] offset:512
	global_load_dword v3, v133, s[44:45] offset:768
	global_load_dword v4, v133, s[44:45] offset:1024
	global_load_dword v5, v133, s[44:45] offset:1280
	global_load_dword v6, v133, s[44:45] offset:1536
	global_load_dword v7, v133, s[44:45] offset:1792
	global_load_dword v8, v133, s[44:45] offset:2048
	global_load_dword v9, v133, s[44:45] offset:2304
	global_load_dword v10, v133, s[44:45] offset:2560
	global_load_dword v11, v133, s[44:45] offset:2816
	global_load_dword v12, v133, s[44:45] offset:3072
	global_load_dword v13, v133, s[44:45] offset:3328
	global_load_dword v14, v133, s[44:45] offset:3584
	global_load_dword v15, v133, s[44:45] offset:3840
	s_add_u32 s44, s44, 0x1000
	s_addc_u32 s45, s45, 0
	s_cmpk_le_u32 s34, 16
	s_cbranch_scc1 .Lsel_ld_done
	global_load_dword v16, v133, s[44:45]
	global_load_dword v17, v133, s[44:45] offset:256
	global_load_dword v18, v133, s[44:45] offset:512
	global_load_dword v19, v133, s[44:45] offset:768
	global_load_dword v20, v133, s[44:45] offset:1024
	global_load_dword v21, v133, s[44:45] offset:1280
	global_load_dword v22, v133, s[44:45] offset:1536
	global_load_dword v23, v133, s[44:45] offset:1792
	global_load_dword v24, v133, s[44:45] offset:2048
	global_load_dword v25, v133, s[44:45] offset:2304
	global_load_dword v26, v133, s[44:45] offset:2560
	global_load_dword v27, v133, s[44:45] offset:2816
	global_load_dword v28, v133, s[44:45] offset:3072
	global_load_dword v29, v133, s[44:45] offset:3328
	global_load_dword v30, v133, s[44:45] offset:3584
	global_load_dword v31, v133, s[44:45] offset:3840
	s_add_u32 s44, s44, 0x1000
	s_addc_u32 s45, s45, 0
	s_cmpk_le_u32 s34, 32
	s_cbranch_scc1 .Lsel_ld_done
	global_load_dword v32, v133, s[44:45]
	global_load_dword v33, v133, s[44:45] offset:256
	global_load_dword v34, v133, s[44:45] offset:512
	global_load_dword v35, v133, s[44:45] offset:768
	global_load_dword v36, v133, s[44:45] offset:1024
	global_load_dword v37, v133, s[44:45] offset:1280
	global_load_dword v38, v133, s[44:45] offset:1536
	global_load_dword v39, v133, s[44:45] offset:1792
	global_load_dword v40, v133, s[44:45] offset:2048
	global_load_dword v41, v133, s[44:45] offset:2304
	global_load_dword v42, v133, s[44:45] offset:2560
	global_load_dword v43, v133, s[44:45] offset:2816
	global_load_dword v44, v133, s[44:45] offset:3072
	global_load_dword v45, v133, s[44:45] offset:3328
	global_load_dword v46, v133, s[44:45] offset:3584
	global_load_dword v47, v133, s[44:45] offset:3840
	s_add_u32 s44, s44, 0x1000
	s_addc_u32 s45, s45, 0
	s_cmpk_le_u32 s34, 48
	s_cbranch_scc1 .Lsel_ld_done
	global_load_dword v48, v133, s[44:45]
	global_load_dword v49, v133, s[44:45] offset:256
	global_load_dword v50, v133, s[44:45] offset:512
	global_load_dword v51, v133, s[44:45] offset:768
	global_load_dword v52, v133, s[44:45] offset:1024
	global_load_dword v53, v133, s[44:45] offset:1280
	global_load_dword v54, v133, s[44:45] offset:1536
	global_load_dword v55, v133, s[44:45] offset:1792
	global_load_dword v56, v133, s[44:45] offset:2048
	global_load_dword v57, v133, s[44:45] offset:2304
	global_load_dword v58, v133, s[44:45] offset:2560
	global_load_dword v59, v133, s[44:45] offset:2816
	global_load_dword v60, v133, s[44:45] offset:3072
	global_load_dword v61, v133, s[44:45] offset:3328
	global_load_dword v62, v133, s[44:45] offset:3584
	global_load_dword v63, v133, s[44:45] offset:3840
	s_add_u32 s44, s44, 0x1000
	s_addc_u32 s45, s45, 0
	s_cmpk_le_u32 s34, 64
	s_cbranch_scc1 .Lsel_ld_done
	global_load_dword v64, v133, s[44:45]
	global_load_dword v65, v133, s[44:45] offset:256
	global_load_dword v66, v133, s[44:45] offset:512
	global_load_dword v67, v133, s[44:45] offset:768
	global_load_dword v68, v133, s[44:45] offset:1024
	global_load_dword v69, v133, s[44:45] offset:1280
	global_load_dword v70, v133, s[44:45] offset:1536
	global_load_dword v71, v133, s[44:45] offset:1792
	global_load_dword v72, v133, s[44:45] offset:2048
	global_load_dword v73, v133, s[44:45] offset:2304
	global_load_dword v74, v133, s[44:45] offset:2560
	global_load_dword v75, v133, s[44:45] offset:2816
	global_load_dword v76, v133, s[44:45] offset:3072
	global_load_dword v77, v133, s[44:45] offset:3328
	global_load_dword v78, v133, s[44:45] offset:3584
	global_load_dword v79, v133, s[44:45] offset:3840
	s_add_u32 s44, s44, 0x1000
	s_addc_u32 s45, s45, 0
	s_cmpk_le_u32 s34, 80
	s_cbranch_scc1 .Lsel_ld_done
	global_load_dword v80, v133, s[44:45]
	global_load_dword v81, v133, s[44:45] offset:256
	global_load_dword v82, v133, s[44:45] offset:512
	global_load_dword v83, v133, s[44:45] offset:768
	global_load_dword v84, v133, s[44:45] offset:1024
	global_load_dword v85, v133, s[44:45] offset:1280
	global_load_dword v86, v133, s[44:45] offset:1536
	global_load_dword v87, v133, s[44:45] offset:1792
	global_load_dword v88, v133, s[44:45] offset:2048
	global_load_dword v89, v133, s[44:45] offset:2304
	global_load_dword v90, v133, s[44:45] offset:2560
	global_load_dword v91, v133, s[44:45] offset:2816
	global_load_dword v92, v133, s[44:45] offset:3072
	global_load_dword v93, v133, s[44:45] offset:3328
	global_load_dword v94, v133, s[44:45] offset:3584
	global_load_dword v95, v133, s[44:45] offset:3840
	s_add_u32 s44, s44, 0x1000
	s_addc_u32 s45, s45, 0
	s_cmpk_le_u32 s34, 96
	s_cbranch_scc1 .Lsel_ld_done
	global_load_dword v208, v133, s[44:45]
	global_load_dword v209, v133, s[44:45] offset:256
	global_load_dword v210, v133, s[44:45] offset:512
	global_load_dword v211, v133, s[44:45] offset:768
	global_load_dword v212, v133, s[44:45] offset:1024
	global_load_dword v213, v133, s[44:45] offset:1280
	global_load_dword v214, v133, s[44:45] offset:1536
	global_load_dword v215, v133, s[44:45] offset:1792
	global_load_dword v216, v133, s[44:45] offset:2048
	global_load_dword v217, v133, s[44:45] offset:2304
	global_load_dword v218, v133, s[44:45] offset:2560
	global_load_dword v219, v133, s[44:45] offset:2816
	global_load_dword v220, v133, s[44:45] offset:3072
	global_load_dword v221, v133, s[44:45] offset:3328
	global_load_dword v222, v133, s[44:45] offset:3584
	global_load_dword v223, v133, s[44:45] offset:3840
	s_add_u32 s44, s44, 0x1000
	s_addc_u32 s45, s45, 0
	s_cmpk_le_u32 s34, 112
	s_cbranch_scc1 .Lsel_ld_done
	global_load_dword v224, v133, s[44:45]
	global_load_dword v225, v133, s[44:45] offset:256
	global_load_dword v226, v133, s[44:45] offset:512
	global_load_dword v227, v133, s[44:45] offset:768
	global_load_dword v228, v133, s[44:45] offset:1024
	global_load_dword v229, v133, s[44:45] offset:1280
	global_load_dword v230, v133, s[44:45] offset:1536
	global_load_dword v231, v133, s[44:45] offset:1792
	global_load_dword v232, v133, s[44:45] offset:2048
	global_load_dword v233, v133, s[44:45] offset:2304
	global_load_dword v234, v133, s[44:45] offset:2560
	global_load_dword v235, v133, s[44:45] offset:2816
	global_load_dword v236, v133, s[44:45] offset:3072
	global_load_dword v237, v133, s[44:45] offset:3328
	global_load_dword v238, v133, s[44:45] offset:3584
	global_load_dword v239, v133, s[44:45] offset:3840
.Lsel_ld_done:
	s_waitcnt vmcnt(0)
	s_cmpk_ge_u32 s33, 1024
	s_cbranch_scc0 .Lsel_cv_slow0
	v_xor_b32_e32 v240, 0x7fffffff, v0
	v_ashrrev_i32_e32 v241, 31, v0
	v_bfi_b32 v0, v241, v0, v240
	v_xor_b32_e32 v242, 0x7fffffff, v1
	v_ashrrev_i32_e32 v243, 31, v1
	v_bfi_b32 v1, v243, v1, v242
	v_xor_b32_e32 v244, 0x7fffffff, v2
	v_ashrrev_i32_e32 v245, 31, v2
	v_bfi_b32 v2, v245, v2, v244
	v_xor_b32_e32 v246, 0x7fffffff, v3
	v_ashrrev_i32_e32 v247, 31, v3
	v_bfi_b32 v3, v247, v3, v246
	v_xor_b32_e32 v240, 0x7fffffff, v4
	v_ashrrev_i32_e32 v241, 31, v4
	v_bfi_b32 v4, v241, v4, v240
	v_xor_b32_e32 v242, 0x7fffffff, v5
	v_ashrrev_i32_e32 v243, 31, v5
	v_bfi_b32 v5, v243, v5, v242
	v_xor_b32_e32 v244, 0x7fffffff, v6
	v_ashrrev_i32_e32 v245, 31, v6
	v_bfi_b32 v6, v245, v6, v244
	v_xor_b32_e32 v246, 0x7fffffff, v7
	v_ashrrev_i32_e32 v247, 31, v7
	v_bfi_b32 v7, v247, v7, v246
	v_xor_b32_e32 v240, 0x7fffffff, v8
	v_ashrrev_i32_e32 v241, 31, v8
	v_bfi_b32 v8, v241, v8, v240
	v_xor_b32_e32 v242, 0x7fffffff, v9
	v_ashrrev_i32_e32 v243, 31, v9
	v_bfi_b32 v9, v243, v9, v242
	v_xor_b32_e32 v244, 0x7fffffff, v10
	v_ashrrev_i32_e32 v245, 31, v10
	v_bfi_b32 v10, v245, v10, v244
	v_xor_b32_e32 v246, 0x7fffffff, v11
	v_ashrrev_i32_e32 v247, 31, v11
	v_bfi_b32 v11, v247, v11, v246
	v_xor_b32_e32 v240, 0x7fffffff, v12
	v_ashrrev_i32_e32 v241, 31, v12
	v_bfi_b32 v12, v241, v12, v240
	v_xor_b32_e32 v242, 0x7fffffff, v13
	v_ashrrev_i32_e32 v243, 31, v13
	v_bfi_b32 v13, v243, v13, v242
	v_xor_b32_e32 v244, 0x7fffffff, v14
	v_ashrrev_i32_e32 v245, 31, v14
	v_bfi_b32 v14, v245, v14, v244
	v_xor_b32_e32 v246, 0x7fffffff, v15
	v_ashrrev_i32_e32 v247, 31, v15
	v_bfi_b32 v15, v247, v15, v246
	s_branch .Lsel_cv_next0
.Lsel_cv_slow0:
	v_cmp_lt_i32_e32 vcc, 0, v138
	v_xor_b32_e32 v240, 0x7fffffff, v0
	v_ashrrev_i32_e32 v241, 31, v0
	v_bfi_b32 v0, v241, v0, v240
	v_cndmask_b32_e32 v0, -1, v0, vcc
	v_cmp_lt_i32_e32 vcc, 64, v138
	v_xor_b32_e32 v242, 0x7fffffff, v1
	v_ashrrev_i32_e32 v243, 31, v1
	v_bfi_b32 v1, v243, v1, v242
	v_cndmask_b32_e32 v1, -1, v1, vcc
	v_cmp_lt_i32_e32 vcc, 0x80, v138
	v_xor_b32_e32 v244, 0x7fffffff, v2
	v_ashrrev_i32_e32 v245, 31, v2
	v_bfi_b32 v2, v245, v2, v244
	v_cndmask_b32_e32 v2, -1, v2, vcc
	v_cmp_lt_i32_e32 vcc, 0xc0, v138
	v_xor_b32_e32 v246, 0x7fffffff, v3
	v_ashrrev_i32_e32 v247, 31, v3
	v_bfi_b32 v3, v247, v3, v246
	v_cndmask_b32_e32 v3, -1, v3, vcc
	v_cmp_lt_i32_e32 vcc, 0x100, v138
	v_xor_b32_e32 v240, 0x7fffffff, v4
	v_ashrrev_i32_e32 v241, 31, v4
	v_bfi_b32 v4, v241, v4, v240
	v_cndmask_b32_e32 v4, -1, v4, vcc
	v_cmp_lt_i32_e32 vcc, 0x140, v138
	v_xor_b32_e32 v242, 0x7fffffff, v5
	v_ashrrev_i32_e32 v243, 31, v5
	v_bfi_b32 v5, v243, v5, v242
	v_cndmask_b32_e32 v5, -1, v5, vcc
	v_cmp_lt_i32_e32 vcc, 0x180, v138
	v_xor_b32_e32 v244, 0x7fffffff, v6
	v_ashrrev_i32_e32 v245, 31, v6
	v_bfi_b32 v6, v245, v6, v244
	v_cndmask_b32_e32 v6, -1, v6, vcc
	v_cmp_lt_i32_e32 vcc, 0x1c0, v138
	v_xor_b32_e32 v246, 0x7fffffff, v7
	v_ashrrev_i32_e32 v247, 31, v7
	v_bfi_b32 v7, v247, v7, v246
	v_cndmask_b32_e32 v7, -1, v7, vcc
	v_cmp_lt_i32_e32 vcc, 0x200, v138
	v_xor_b32_e32 v240, 0x7fffffff, v8
	v_ashrrev_i32_e32 v241, 31, v8
	v_bfi_b32 v8, v241, v8, v240
	v_cndmask_b32_e32 v8, -1, v8, vcc
	v_cmp_lt_i32_e32 vcc, 0x240, v138
	v_xor_b32_e32 v242, 0x7fffffff, v9
	v_ashrrev_i32_e32 v243, 31, v9
	v_bfi_b32 v9, v243, v9, v242
	v_cndmask_b32_e32 v9, -1, v9, vcc
	v_cmp_lt_i32_e32 vcc, 0x280, v138
	v_xor_b32_e32 v244, 0x7fffffff, v10
	v_ashrrev_i32_e32 v245, 31, v10
	v_bfi_b32 v10, v245, v10, v244
	v_cndmask_b32_e32 v10, -1, v10, vcc
	v_cmp_lt_i32_e32 vcc, 0x2c0, v138
	v_xor_b32_e32 v246, 0x7fffffff, v11
	v_ashrrev_i32_e32 v247, 31, v11
	v_bfi_b32 v11, v247, v11, v246
	v_cndmask_b32_e32 v11, -1, v11, vcc
	v_cmp_lt_i32_e32 vcc, 0x300, v138
	v_xor_b32_e32 v240, 0x7fffffff, v12
	v_ashrrev_i32_e32 v241, 31, v12
	v_bfi_b32 v12, v241, v12, v240
	v_cndmask_b32_e32 v12, -1, v12, vcc
	v_cmp_lt_i32_e32 vcc, 0x340, v138
	v_xor_b32_e32 v242, 0x7fffffff, v13
	v_ashrrev_i32_e32 v243, 31, v13
	v_bfi_b32 v13, v243, v13, v242
	v_cndmask_b32_e32 v13, -1, v13, vcc
	v_cmp_lt_i32_e32 vcc, 0x380, v138
	v_xor_b32_e32 v244, 0x7fffffff, v14
	v_ashrrev_i32_e32 v245, 31, v14
	v_bfi_b32 v14, v245, v14, v244
	v_cndmask_b32_e32 v14, -1, v14, vcc
	v_cmp_lt_i32_e32 vcc, 0x3c0, v138
	v_xor_b32_e32 v246, 0x7fffffff, v15
	v_ashrrev_i32_e32 v247, 31, v15
	v_bfi_b32 v15, v247, v15, v246
	v_cndmask_b32_e32 v15, -1, v15, vcc
.Lsel_cv_next0:
	s_cmpk_le_u32 s34, 16
	s_cbranch_scc1 .Lsel_cv_done
	s_cmpk_ge_u32 s33, 2048
	s_cbranch_scc0 .Lsel_cv_slow1
	v_xor_b32_e32 v240, 0x7fffffff, v16
	v_ashrrev_i32_e32 v241, 31, v16
	v_bfi_b32 v16, v241, v16, v240
	v_xor_b32_e32 v242, 0x7fffffff, v17
	v_ashrrev_i32_e32 v243, 31, v17
	v_bfi_b32 v17, v243, v17, v242
	v_xor_b32_e32 v244, 0x7fffffff, v18
	v_ashrrev_i32_e32 v245, 31, v18
	v_bfi_b32 v18, v245, v18, v244
	v_xor_b32_e32 v246, 0x7fffffff, v19
	v_ashrrev_i32_e32 v247, 31, v19
	v_bfi_b32 v19, v247, v19, v246
	v_xor_b32_e32 v240, 0x7fffffff, v20
	v_ashrrev_i32_e32 v241, 31, v20
	v_bfi_b32 v20, v241, v20, v240
	v_xor_b32_e32 v242, 0x7fffffff, v21
	v_ashrrev_i32_e32 v243, 31, v21
	v_bfi_b32 v21, v243, v21, v242
	v_xor_b32_e32 v244, 0x7fffffff, v22
	v_ashrrev_i32_e32 v245, 31, v22
	v_bfi_b32 v22, v245, v22, v244
	v_xor_b32_e32 v246, 0x7fffffff, v23
	v_ashrrev_i32_e32 v247, 31, v23
	v_bfi_b32 v23, v247, v23, v246
	v_xor_b32_e32 v240, 0x7fffffff, v24
	v_ashrrev_i32_e32 v241, 31, v24
	v_bfi_b32 v24, v241, v24, v240
	v_xor_b32_e32 v242, 0x7fffffff, v25
	v_ashrrev_i32_e32 v243, 31, v25
	v_bfi_b32 v25, v243, v25, v242
	v_xor_b32_e32 v244, 0x7fffffff, v26
	v_ashrrev_i32_e32 v245, 31, v26
	v_bfi_b32 v26, v245, v26, v244
	v_xor_b32_e32 v246, 0x7fffffff, v27
	v_ashrrev_i32_e32 v247, 31, v27
	v_bfi_b32 v27, v247, v27, v246
	v_xor_b32_e32 v240, 0x7fffffff, v28
	v_ashrrev_i32_e32 v241, 31, v28
	v_bfi_b32 v28, v241, v28, v240
	v_xor_b32_e32 v242, 0x7fffffff, v29
	v_ashrrev_i32_e32 v243, 31, v29
	v_bfi_b32 v29, v243, v29, v242
	v_xor_b32_e32 v244, 0x7fffffff, v30
	v_ashrrev_i32_e32 v245, 31, v30
	v_bfi_b32 v30, v245, v30, v244
	v_xor_b32_e32 v246, 0x7fffffff, v31
	v_ashrrev_i32_e32 v247, 31, v31
	v_bfi_b32 v31, v247, v31, v246
	s_branch .Lsel_cv_next1
.Lsel_cv_slow1:
	v_cmp_lt_i32_e32 vcc, 0x400, v138
	v_xor_b32_e32 v240, 0x7fffffff, v16
	v_ashrrev_i32_e32 v241, 31, v16
	v_bfi_b32 v16, v241, v16, v240
	v_cndmask_b32_e32 v16, -1, v16, vcc
	v_cmp_lt_i32_e32 vcc, 0x440, v138
	v_xor_b32_e32 v242, 0x7fffffff, v17
	v_ashrrev_i32_e32 v243, 31, v17
	v_bfi_b32 v17, v243, v17, v242
	v_cndmask_b32_e32 v17, -1, v17, vcc
	v_cmp_lt_i32_e32 vcc, 0x480, v138
	v_xor_b32_e32 v244, 0x7fffffff, v18
	v_ashrrev_i32_e32 v245, 31, v18
	v_bfi_b32 v18, v245, v18, v244
	v_cndmask_b32_e32 v18, -1, v18, vcc
	v_cmp_lt_i32_e32 vcc, 0x4c0, v138
	v_xor_b32_e32 v246, 0x7fffffff, v19
	v_ashrrev_i32_e32 v247, 31, v19
	v_bfi_b32 v19, v247, v19, v246
	v_cndmask_b32_e32 v19, -1, v19, vcc
	v_cmp_lt_i32_e32 vcc, 0x500, v138
	v_xor_b32_e32 v240, 0x7fffffff, v20
	v_ashrrev_i32_e32 v241, 31, v20
	v_bfi_b32 v20, v241, v20, v240
	v_cndmask_b32_e32 v20, -1, v20, vcc
	v_cmp_lt_i32_e32 vcc, 0x540, v138
	v_xor_b32_e32 v242, 0x7fffffff, v21
	v_ashrrev_i32_e32 v243, 31, v21
	v_bfi_b32 v21, v243, v21, v242
	v_cndmask_b32_e32 v21, -1, v21, vcc
	v_cmp_lt_i32_e32 vcc, 0x580, v138
	v_xor_b32_e32 v244, 0x7fffffff, v22
	v_ashrrev_i32_e32 v245, 31, v22
	v_bfi_b32 v22, v245, v22, v244
	v_cndmask_b32_e32 v22, -1, v22, vcc
	v_cmp_lt_i32_e32 vcc, 0x5c0, v138
	v_xor_b32_e32 v246, 0x7fffffff, v23
	v_ashrrev_i32_e32 v247, 31, v23
	v_bfi_b32 v23, v247, v23, v246
	v_cndmask_b32_e32 v23, -1, v23, vcc
	v_cmp_lt_i32_e32 vcc, 0x600, v138
	v_xor_b32_e32 v240, 0x7fffffff, v24
	v_ashrrev_i32_e32 v241, 31, v24
	v_bfi_b32 v24, v241, v24, v240
	v_cndmask_b32_e32 v24, -1, v24, vcc
	v_cmp_lt_i32_e32 vcc, 0x640, v138
	v_xor_b32_e32 v242, 0x7fffffff, v25
	v_ashrrev_i32_e32 v243, 31, v25
	v_bfi_b32 v25, v243, v25, v242
	v_cndmask_b32_e32 v25, -1, v25, vcc
	v_cmp_lt_i32_e32 vcc, 0x680, v138
	v_xor_b32_e32 v244, 0x7fffffff, v26
	v_ashrrev_i32_e32 v245, 31, v26
	v_bfi_b32 v26, v245, v26, v244
	v_cndmask_b32_e32 v26, -1, v26, vcc
	v_cmp_lt_i32_e32 vcc, 0x6c0, v138
	v_xor_b32_e32 v246, 0x7fffffff, v27
	v_ashrrev_i32_e32 v247, 31, v27
	v_bfi_b32 v27, v247, v27, v246
	v_cndmask_b32_e32 v27, -1, v27, vcc
	v_cmp_lt_i32_e32 vcc, 0x700, v138
	v_xor_b32_e32 v240, 0x7fffffff, v28
	v_ashrrev_i32_e32 v241, 31, v28
	v_bfi_b32 v28, v241, v28, v240
	v_cndmask_b32_e32 v28, -1, v28, vcc
	v_cmp_lt_i32_e32 vcc, 0x740, v138
	v_xor_b32_e32 v242, 0x7fffffff, v29
	v_ashrrev_i32_e32 v243, 31, v29
	v_bfi_b32 v29, v243, v29, v242
	v_cndmask_b32_e32 v29, -1, v29, vcc
	v_cmp_lt_i32_e32 vcc, 0x780, v138
	v_xor_b32_e32 v244, 0x7fffffff, v30
	v_ashrrev_i32_e32 v245, 31, v30
	v_bfi_b32 v30, v245, v30, v244
	v_cndmask_b32_e32 v30, -1, v30, vcc
	v_cmp_lt_i32_e32 vcc, 0x7c0, v138
	v_xor_b32_e32 v246, 0x7fffffff, v31
	v_ashrrev_i32_e32 v247, 31, v31
	v_bfi_b32 v31, v247, v31, v246
	v_cndmask_b32_e32 v31, -1, v31, vcc
.Lsel_cv_next1:
	s_cmpk_le_u32 s34, 32
	s_cbranch_scc1 .Lsel_cv_done
	s_cmpk_ge_u32 s33, 3072
	s_cbranch_scc0 .Lsel_cv_slow2
	v_xor_b32_e32 v240, 0x7fffffff, v32
	v_ashrrev_i32_e32 v241, 31, v32
	v_bfi_b32 v32, v241, v32, v240
	v_xor_b32_e32 v242, 0x7fffffff, v33
	v_ashrrev_i32_e32 v243, 31, v33
	v_bfi_b32 v33, v243, v33, v242
	v_xor_b32_e32 v244, 0x7fffffff, v34
	v_ashrrev_i32_e32 v245, 31, v34
	v_bfi_b32 v34, v245, v34, v244
	v_xor_b32_e32 v246, 0x7fffffff, v35
	v_ashrrev_i32_e32 v247, 31, v35
	v_bfi_b32 v35, v247, v35, v246
	v_xor_b32_e32 v240, 0x7fffffff, v36
	v_ashrrev_i32_e32 v241, 31, v36
	v_bfi_b32 v36, v241, v36, v240
	v_xor_b32_e32 v242, 0x7fffffff, v37
	v_ashrrev_i32_e32 v243, 31, v37
	v_bfi_b32 v37, v243, v37, v242
	v_xor_b32_e32 v244, 0x7fffffff, v38
	v_ashrrev_i32_e32 v245, 31, v38
	v_bfi_b32 v38, v245, v38, v244
	v_xor_b32_e32 v246, 0x7fffffff, v39
	v_ashrrev_i32_e32 v247, 31, v39
	v_bfi_b32 v39, v247, v39, v246
	v_xor_b32_e32 v240, 0x7fffffff, v40
	v_ashrrev_i32_e32 v241, 31, v40
	v_bfi_b32 v40, v241, v40, v240
	v_xor_b32_e32 v242, 0x7fffffff, v41
	v_ashrrev_i32_e32 v243, 31, v41
	v_bfi_b32 v41, v243, v41, v242
	v_xor_b32_e32 v244, 0x7fffffff, v42
	v_ashrrev_i32_e32 v245, 31, v42
	v_bfi_b32 v42, v245, v42, v244
	v_xor_b32_e32 v246, 0x7fffffff, v43
	v_ashrrev_i32_e32 v247, 31, v43
	v_bfi_b32 v43, v247, v43, v246
	v_xor_b32_e32 v240, 0x7fffffff, v44
	v_ashrrev_i32_e32 v241, 31, v44
	v_bfi_b32 v44, v241, v44, v240
	v_xor_b32_e32 v242, 0x7fffffff, v45
	v_ashrrev_i32_e32 v243, 31, v45
	v_bfi_b32 v45, v243, v45, v242
	v_xor_b32_e32 v244, 0x7fffffff, v46
	v_ashrrev_i32_e32 v245, 31, v46
	v_bfi_b32 v46, v245, v46, v244
	v_xor_b32_e32 v246, 0x7fffffff, v47
	v_ashrrev_i32_e32 v247, 31, v47
	v_bfi_b32 v47, v247, v47, v246
	s_branch .Lsel_cv_next2
.Lsel_cv_slow2:
	v_cmp_lt_i32_e32 vcc, 0x800, v138
	v_xor_b32_e32 v240, 0x7fffffff, v32
	v_ashrrev_i32_e32 v241, 31, v32
	v_bfi_b32 v32, v241, v32, v240
	v_cndmask_b32_e32 v32, -1, v32, vcc
	v_cmp_lt_i32_e32 vcc, 0x840, v138
	v_xor_b32_e32 v242, 0x7fffffff, v33
	v_ashrrev_i32_e32 v243, 31, v33
	v_bfi_b32 v33, v243, v33, v242
	v_cndmask_b32_e32 v33, -1, v33, vcc
	v_cmp_lt_i32_e32 vcc, 0x880, v138
	v_xor_b32_e32 v244, 0x7fffffff, v34
	v_ashrrev_i32_e32 v245, 31, v34
	v_bfi_b32 v34, v245, v34, v244
	v_cndmask_b32_e32 v34, -1, v34, vcc
	v_cmp_lt_i32_e32 vcc, 0x8c0, v138
	v_xor_b32_e32 v246, 0x7fffffff, v35
	v_ashrrev_i32_e32 v247, 31, v35
	v_bfi_b32 v35, v247, v35, v246
	v_cndmask_b32_e32 v35, -1, v35, vcc
	v_cmp_lt_i32_e32 vcc, 0x900, v138
	v_xor_b32_e32 v240, 0x7fffffff, v36
	v_ashrrev_i32_e32 v241, 31, v36
	v_bfi_b32 v36, v241, v36, v240
	v_cndmask_b32_e32 v36, -1, v36, vcc
	v_cmp_lt_i32_e32 vcc, 0x940, v138
	v_xor_b32_e32 v242, 0x7fffffff, v37
	v_ashrrev_i32_e32 v243, 31, v37
	v_bfi_b32 v37, v243, v37, v242
	v_cndmask_b32_e32 v37, -1, v37, vcc
	v_cmp_lt_i32_e32 vcc, 0x980, v138
	v_xor_b32_e32 v244, 0x7fffffff, v38
	v_ashrrev_i32_e32 v245, 31, v38
	v_bfi_b32 v38, v245, v38, v244
	v_cndmask_b32_e32 v38, -1, v38, vcc
	v_cmp_lt_i32_e32 vcc, 0x9c0, v138
	v_xor_b32_e32 v246, 0x7fffffff, v39
	v_ashrrev_i32_e32 v247, 31, v39
	v_bfi_b32 v39, v247, v39, v246
	v_cndmask_b32_e32 v39, -1, v39, vcc
	v_cmp_lt_i32_e32 vcc, 0xa00, v138
	v_xor_b32_e32 v240, 0x7fffffff, v40
	v_ashrrev_i32_e32 v241, 31, v40
	v_bfi_b32 v40, v241, v40, v240
	v_cndmask_b32_e32 v40, -1, v40, vcc
	v_cmp_lt_i32_e32 vcc, 0xa40, v138
	v_xor_b32_e32 v242, 0x7fffffff, v41
	v_ashrrev_i32_e32 v243, 31, v41
	v_bfi_b32 v41, v243, v41, v242
	v_cndmask_b32_e32 v41, -1, v41, vcc
	v_cmp_lt_i32_e32 vcc, 0xa80, v138
	v_xor_b32_e32 v244, 0x7fffffff, v42
	v_ashrrev_i32_e32 v245, 31, v42
	v_bfi_b32 v42, v245, v42, v244
	v_cndmask_b32_e32 v42, -1, v42, vcc
	v_cmp_lt_i32_e32 vcc, 0xac0, v138
	v_xor_b32_e32 v246, 0x7fffffff, v43
	v_ashrrev_i32_e32 v247, 31, v43
	v_bfi_b32 v43, v247, v43, v246
	v_cndmask_b32_e32 v43, -1, v43, vcc
	v_cmp_lt_i32_e32 vcc, 0xb00, v138
	v_xor_b32_e32 v240, 0x7fffffff, v44
	v_ashrrev_i32_e32 v241, 31, v44
	v_bfi_b32 v44, v241, v44, v240
	v_cndmask_b32_e32 v44, -1, v44, vcc
	v_cmp_lt_i32_e32 vcc, 0xb40, v138
	v_xor_b32_e32 v242, 0x7fffffff, v45
	v_ashrrev_i32_e32 v243, 31, v45
	v_bfi_b32 v45, v243, v45, v242
	v_cndmask_b32_e32 v45, -1, v45, vcc
	v_cmp_lt_i32_e32 vcc, 0xb80, v138
	v_xor_b32_e32 v244, 0x7fffffff, v46
	v_ashrrev_i32_e32 v245, 31, v46
	v_bfi_b32 v46, v245, v46, v244
	v_cndmask_b32_e32 v46, -1, v46, vcc
	v_cmp_lt_i32_e32 vcc, 0xbc0, v138
	v_xor_b32_e32 v246, 0x7fffffff, v47
	v_ashrrev_i32_e32 v247, 31, v47
	v_bfi_b32 v47, v247, v47, v246
	v_cndmask_b32_e32 v47, -1, v47, vcc
.Lsel_cv_next2:
	s_cmpk_le_u32 s34, 48
	s_cbranch_scc1 .Lsel_cv_done
	s_cmpk_ge_u32 s33, 4096
	s_cbranch_scc0 .Lsel_cv_slow3
	v_xor_b32_e32 v240, 0x7fffffff, v48
	v_ashrrev_i32_e32 v241, 31, v48
	v_bfi_b32 v48, v241, v48, v240
	v_xor_b32_e32 v242, 0x7fffffff, v49
	v_ashrrev_i32_e32 v243, 31, v49
	v_bfi_b32 v49, v243, v49, v242
	v_xor_b32_e32 v244, 0x7fffffff, v50
	v_ashrrev_i32_e32 v245, 31, v50
	v_bfi_b32 v50, v245, v50, v244
	v_xor_b32_e32 v246, 0x7fffffff, v51
	v_ashrrev_i32_e32 v247, 31, v51
	v_bfi_b32 v51, v247, v51, v246
	v_xor_b32_e32 v240, 0x7fffffff, v52
	v_ashrrev_i32_e32 v241, 31, v52
	v_bfi_b32 v52, v241, v52, v240
	v_xor_b32_e32 v242, 0x7fffffff, v53
	v_ashrrev_i32_e32 v243, 31, v53
	v_bfi_b32 v53, v243, v53, v242
	v_xor_b32_e32 v244, 0x7fffffff, v54
	v_ashrrev_i32_e32 v245, 31, v54
	v_bfi_b32 v54, v245, v54, v244
	v_xor_b32_e32 v246, 0x7fffffff, v55
	v_ashrrev_i32_e32 v247, 31, v55
	v_bfi_b32 v55, v247, v55, v246
	v_xor_b32_e32 v240, 0x7fffffff, v56
	v_ashrrev_i32_e32 v241, 31, v56
	v_bfi_b32 v56, v241, v56, v240
	v_xor_b32_e32 v242, 0x7fffffff, v57
	v_ashrrev_i32_e32 v243, 31, v57
	v_bfi_b32 v57, v243, v57, v242
	v_xor_b32_e32 v244, 0x7fffffff, v58
	v_ashrrev_i32_e32 v245, 31, v58
	v_bfi_b32 v58, v245, v58, v244
	v_xor_b32_e32 v246, 0x7fffffff, v59
	v_ashrrev_i32_e32 v247, 31, v59
	v_bfi_b32 v59, v247, v59, v246
	v_xor_b32_e32 v240, 0x7fffffff, v60
	v_ashrrev_i32_e32 v241, 31, v60
	v_bfi_b32 v60, v241, v60, v240
	v_xor_b32_e32 v242, 0x7fffffff, v61
	v_ashrrev_i32_e32 v243, 31, v61
	v_bfi_b32 v61, v243, v61, v242
	v_xor_b32_e32 v244, 0x7fffffff, v62
	v_ashrrev_i32_e32 v245, 31, v62
	v_bfi_b32 v62, v245, v62, v244
	v_xor_b32_e32 v246, 0x7fffffff, v63
	v_ashrrev_i32_e32 v247, 31, v63
	v_bfi_b32 v63, v247, v63, v246
	s_branch .Lsel_cv_next3
.Lsel_cv_slow3:
	v_cmp_lt_i32_e32 vcc, 0xc00, v138
	v_xor_b32_e32 v240, 0x7fffffff, v48
	v_ashrrev_i32_e32 v241, 31, v48
	v_bfi_b32 v48, v241, v48, v240
	v_cndmask_b32_e32 v48, -1, v48, vcc
	v_cmp_lt_i32_e32 vcc, 0xc40, v138
	v_xor_b32_e32 v242, 0x7fffffff, v49
	v_ashrrev_i32_e32 v243, 31, v49
	v_bfi_b32 v49, v243, v49, v242
	v_cndmask_b32_e32 v49, -1, v49, vcc
	v_cmp_lt_i32_e32 vcc, 0xc80, v138
	v_xor_b32_e32 v244, 0x7fffffff, v50
	v_ashrrev_i32_e32 v245, 31, v50
	v_bfi_b32 v50, v245, v50, v244
	v_cndmask_b32_e32 v50, -1, v50, vcc
	v_cmp_lt_i32_e32 vcc, 0xcc0, v138
	v_xor_b32_e32 v246, 0x7fffffff, v51
	v_ashrrev_i32_e32 v247, 31, v51
	v_bfi_b32 v51, v247, v51, v246
	v_cndmask_b32_e32 v51, -1, v51, vcc
	v_cmp_lt_i32_e32 vcc, 0xd00, v138
	v_xor_b32_e32 v240, 0x7fffffff, v52
	v_ashrrev_i32_e32 v241, 31, v52
	v_bfi_b32 v52, v241, v52, v240
	v_cndmask_b32_e32 v52, -1, v52, vcc
	v_cmp_lt_i32_e32 vcc, 0xd40, v138
	v_xor_b32_e32 v242, 0x7fffffff, v53
	v_ashrrev_i32_e32 v243, 31, v53
	v_bfi_b32 v53, v243, v53, v242
	v_cndmask_b32_e32 v53, -1, v53, vcc
	v_cmp_lt_i32_e32 vcc, 0xd80, v138
	v_xor_b32_e32 v244, 0x7fffffff, v54
	v_ashrrev_i32_e32 v245, 31, v54
	v_bfi_b32 v54, v245, v54, v244
	v_cndmask_b32_e32 v54, -1, v54, vcc
	v_cmp_lt_i32_e32 vcc, 0xdc0, v138
	v_xor_b32_e32 v246, 0x7fffffff, v55
	v_ashrrev_i32_e32 v247, 31, v55
	v_bfi_b32 v55, v247, v55, v246
	v_cndmask_b32_e32 v55, -1, v55, vcc
	v_cmp_lt_i32_e32 vcc, 0xe00, v138
	v_xor_b32_e32 v240, 0x7fffffff, v56
	v_ashrrev_i32_e32 v241, 31, v56
	v_bfi_b32 v56, v241, v56, v240
	v_cndmask_b32_e32 v56, -1, v56, vcc
	v_cmp_lt_i32_e32 vcc, 0xe40, v138
	v_xor_b32_e32 v242, 0x7fffffff, v57
	v_ashrrev_i32_e32 v243, 31, v57
	v_bfi_b32 v57, v243, v57, v242
	v_cndmask_b32_e32 v57, -1, v57, vcc
	v_cmp_lt_i32_e32 vcc, 0xe80, v138
	v_xor_b32_e32 v244, 0x7fffffff, v58
	v_ashrrev_i32_e32 v245, 31, v58
	v_bfi_b32 v58, v245, v58, v244
	v_cndmask_b32_e32 v58, -1, v58, vcc
	v_cmp_lt_i32_e32 vcc, 0xec0, v138
	v_xor_b32_e32 v246, 0x7fffffff, v59
	v_ashrrev_i32_e32 v247, 31, v59
	v_bfi_b32 v59, v247, v59, v246
	v_cndmask_b32_e32 v59, -1, v59, vcc
	v_cmp_lt_i32_e32 vcc, 0xf00, v138
	v_xor_b32_e32 v240, 0x7fffffff, v60
	v_ashrrev_i32_e32 v241, 31, v60
	v_bfi_b32 v60, v241, v60, v240
	v_cndmask_b32_e32 v60, -1, v60, vcc
	v_cmp_lt_i32_e32 vcc, 0xf40, v138
	v_xor_b32_e32 v242, 0x7fffffff, v61
	v_ashrrev_i32_e32 v243, 31, v61
	v_bfi_b32 v61, v243, v61, v242
	v_cndmask_b32_e32 v61, -1, v61, vcc
	v_cmp_lt_i32_e32 vcc, 0xf80, v138
	v_xor_b32_e32 v244, 0x7fffffff, v62
	v_ashrrev_i32_e32 v245, 31, v62
	v_bfi_b32 v62, v245, v62, v244
	v_cndmask_b32_e32 v62, -1, v62, vcc
	v_cmp_lt_i32_e32 vcc, 0xfc0, v138
	v_xor_b32_e32 v246, 0x7fffffff, v63
	v_ashrrev_i32_e32 v247, 31, v63
	v_bfi_b32 v63, v247, v63, v246
	v_cndmask_b32_e32 v63, -1, v63, vcc
.Lsel_cv_next3:
	s_cmpk_le_u32 s34, 64
	s_cbranch_scc1 .Lsel_cv_done
	s_cmpk_ge_u32 s33, 5120
	s_cbranch_scc0 .Lsel_cv_slow4
	v_xor_b32_e32 v240, 0x7fffffff, v64
	v_ashrrev_i32_e32 v241, 31, v64
	v_bfi_b32 v64, v241, v64, v240
	v_xor_b32_e32 v242, 0x7fffffff, v65
	v_ashrrev_i32_e32 v243, 31, v65
	v_bfi_b32 v65, v243, v65, v242
	v_xor_b32_e32 v244, 0x7fffffff, v66
	v_ashrrev_i32_e32 v245, 31, v66
	v_bfi_b32 v66, v245, v66, v244
	v_xor_b32_e32 v246, 0x7fffffff, v67
	v_ashrrev_i32_e32 v247, 31, v67
	v_bfi_b32 v67, v247, v67, v246
	v_xor_b32_e32 v240, 0x7fffffff, v68
	v_ashrrev_i32_e32 v241, 31, v68
	v_bfi_b32 v68, v241, v68, v240
	v_xor_b32_e32 v242, 0x7fffffff, v69
	v_ashrrev_i32_e32 v243, 31, v69
	v_bfi_b32 v69, v243, v69, v242
	v_xor_b32_e32 v244, 0x7fffffff, v70
	v_ashrrev_i32_e32 v245, 31, v70
	v_bfi_b32 v70, v245, v70, v244
	v_xor_b32_e32 v246, 0x7fffffff, v71
	v_ashrrev_i32_e32 v247, 31, v71
	v_bfi_b32 v71, v247, v71, v246
	v_xor_b32_e32 v240, 0x7fffffff, v72
	v_ashrrev_i32_e32 v241, 31, v72
	v_bfi_b32 v72, v241, v72, v240
	v_xor_b32_e32 v242, 0x7fffffff, v73
	v_ashrrev_i32_e32 v243, 31, v73
	v_bfi_b32 v73, v243, v73, v242
	v_xor_b32_e32 v244, 0x7fffffff, v74
	v_ashrrev_i32_e32 v245, 31, v74
	v_bfi_b32 v74, v245, v74, v244
	v_xor_b32_e32 v246, 0x7fffffff, v75
	v_ashrrev_i32_e32 v247, 31, v75
	v_bfi_b32 v75, v247, v75, v246
	v_xor_b32_e32 v240, 0x7fffffff, v76
	v_ashrrev_i32_e32 v241, 31, v76
	v_bfi_b32 v76, v241, v76, v240
	v_xor_b32_e32 v242, 0x7fffffff, v77
	v_ashrrev_i32_e32 v243, 31, v77
	v_bfi_b32 v77, v243, v77, v242
	v_xor_b32_e32 v244, 0x7fffffff, v78
	v_ashrrev_i32_e32 v245, 31, v78
	v_bfi_b32 v78, v245, v78, v244
	v_xor_b32_e32 v246, 0x7fffffff, v79
	v_ashrrev_i32_e32 v247, 31, v79
	v_bfi_b32 v79, v247, v79, v246
	s_branch .Lsel_cv_next4
.Lsel_cv_slow4:
	v_cmp_lt_i32_e32 vcc, 0x1000, v138
	v_xor_b32_e32 v240, 0x7fffffff, v64
	v_ashrrev_i32_e32 v241, 31, v64
	v_bfi_b32 v64, v241, v64, v240
	v_cndmask_b32_e32 v64, -1, v64, vcc
	v_cmp_lt_i32_e32 vcc, 0x1040, v138
	v_xor_b32_e32 v242, 0x7fffffff, v65
	v_ashrrev_i32_e32 v243, 31, v65
	v_bfi_b32 v65, v243, v65, v242
	v_cndmask_b32_e32 v65, -1, v65, vcc
	v_cmp_lt_i32_e32 vcc, 0x1080, v138
	v_xor_b32_e32 v244, 0x7fffffff, v66
	v_ashrrev_i32_e32 v245, 31, v66
	v_bfi_b32 v66, v245, v66, v244
	v_cndmask_b32_e32 v66, -1, v66, vcc
	v_cmp_lt_i32_e32 vcc, 0x10c0, v138
	v_xor_b32_e32 v246, 0x7fffffff, v67
	v_ashrrev_i32_e32 v247, 31, v67
	v_bfi_b32 v67, v247, v67, v246
	v_cndmask_b32_e32 v67, -1, v67, vcc
	v_cmp_lt_i32_e32 vcc, 0x1100, v138
	v_xor_b32_e32 v240, 0x7fffffff, v68
	v_ashrrev_i32_e32 v241, 31, v68
	v_bfi_b32 v68, v241, v68, v240
	v_cndmask_b32_e32 v68, -1, v68, vcc
	v_cmp_lt_i32_e32 vcc, 0x1140, v138
	v_xor_b32_e32 v242, 0x7fffffff, v69
	v_ashrrev_i32_e32 v243, 31, v69
	v_bfi_b32 v69, v243, v69, v242
	v_cndmask_b32_e32 v69, -1, v69, vcc
	v_cmp_lt_i32_e32 vcc, 0x1180, v138
	v_xor_b32_e32 v244, 0x7fffffff, v70
	v_ashrrev_i32_e32 v245, 31, v70
	v_bfi_b32 v70, v245, v70, v244
	v_cndmask_b32_e32 v70, -1, v70, vcc
	v_cmp_lt_i32_e32 vcc, 0x11c0, v138
	v_xor_b32_e32 v246, 0x7fffffff, v71
	v_ashrrev_i32_e32 v247, 31, v71
	v_bfi_b32 v71, v247, v71, v246
	v_cndmask_b32_e32 v71, -1, v71, vcc
	v_cmp_lt_i32_e32 vcc, 0x1200, v138
	v_xor_b32_e32 v240, 0x7fffffff, v72
	v_ashrrev_i32_e32 v241, 31, v72
	v_bfi_b32 v72, v241, v72, v240
	v_cndmask_b32_e32 v72, -1, v72, vcc
	v_cmp_lt_i32_e32 vcc, 0x1240, v138
	v_xor_b32_e32 v242, 0x7fffffff, v73
	v_ashrrev_i32_e32 v243, 31, v73
	v_bfi_b32 v73, v243, v73, v242
	v_cndmask_b32_e32 v73, -1, v73, vcc
	v_cmp_lt_i32_e32 vcc, 0x1280, v138
	v_xor_b32_e32 v244, 0x7fffffff, v74
	v_ashrrev_i32_e32 v245, 31, v74
	v_bfi_b32 v74, v245, v74, v244
	v_cndmask_b32_e32 v74, -1, v74, vcc
	v_cmp_lt_i32_e32 vcc, 0x12c0, v138
	v_xor_b32_e32 v246, 0x7fffffff, v75
	v_ashrrev_i32_e32 v247, 31, v75
	v_bfi_b32 v75, v247, v75, v246
	v_cndmask_b32_e32 v75, -1, v75, vcc
	v_cmp_lt_i32_e32 vcc, 0x1300, v138
	v_xor_b32_e32 v240, 0x7fffffff, v76
	v_ashrrev_i32_e32 v241, 31, v76
	v_bfi_b32 v76, v241, v76, v240
	v_cndmask_b32_e32 v76, -1, v76, vcc
	v_cmp_lt_i32_e32 vcc, 0x1340, v138
	v_xor_b32_e32 v242, 0x7fffffff, v77
	v_ashrrev_i32_e32 v243, 31, v77
	v_bfi_b32 v77, v243, v77, v242
	v_cndmask_b32_e32 v77, -1, v77, vcc
	v_cmp_lt_i32_e32 vcc, 0x1380, v138
	v_xor_b32_e32 v244, 0x7fffffff, v78
	v_ashrrev_i32_e32 v245, 31, v78
	v_bfi_b32 v78, v245, v78, v244
	v_cndmask_b32_e32 v78, -1, v78, vcc
	v_cmp_lt_i32_e32 vcc, 0x13c0, v138
	v_xor_b32_e32 v246, 0x7fffffff, v79
	v_ashrrev_i32_e32 v247, 31, v79
	v_bfi_b32 v79, v247, v79, v246
	v_cndmask_b32_e32 v79, -1, v79, vcc
.Lsel_cv_next4:
	s_cmpk_le_u32 s34, 80
	s_cbranch_scc1 .Lsel_cv_done
	s_cmpk_ge_u32 s33, 6144
	s_cbranch_scc0 .Lsel_cv_slow5
	v_xor_b32_e32 v240, 0x7fffffff, v80
	v_ashrrev_i32_e32 v241, 31, v80
	v_bfi_b32 v80, v241, v80, v240
	v_xor_b32_e32 v242, 0x7fffffff, v81
	v_ashrrev_i32_e32 v243, 31, v81
	v_bfi_b32 v81, v243, v81, v242
	v_xor_b32_e32 v244, 0x7fffffff, v82
	v_ashrrev_i32_e32 v245, 31, v82
	v_bfi_b32 v82, v245, v82, v244
	v_xor_b32_e32 v246, 0x7fffffff, v83
	v_ashrrev_i32_e32 v247, 31, v83
	v_bfi_b32 v83, v247, v83, v246
	v_xor_b32_e32 v240, 0x7fffffff, v84
	v_ashrrev_i32_e32 v241, 31, v84
	v_bfi_b32 v84, v241, v84, v240
	v_xor_b32_e32 v242, 0x7fffffff, v85
	v_ashrrev_i32_e32 v243, 31, v85
	v_bfi_b32 v85, v243, v85, v242
	v_xor_b32_e32 v244, 0x7fffffff, v86
	v_ashrrev_i32_e32 v245, 31, v86
	v_bfi_b32 v86, v245, v86, v244
	v_xor_b32_e32 v246, 0x7fffffff, v87
	v_ashrrev_i32_e32 v247, 31, v87
	v_bfi_b32 v87, v247, v87, v246
	v_xor_b32_e32 v240, 0x7fffffff, v88
	v_ashrrev_i32_e32 v241, 31, v88
	v_bfi_b32 v88, v241, v88, v240
	v_xor_b32_e32 v242, 0x7fffffff, v89
	v_ashrrev_i32_e32 v243, 31, v89
	v_bfi_b32 v89, v243, v89, v242
	v_xor_b32_e32 v244, 0x7fffffff, v90
	v_ashrrev_i32_e32 v245, 31, v90
	v_bfi_b32 v90, v245, v90, v244
	v_xor_b32_e32 v246, 0x7fffffff, v91
	v_ashrrev_i32_e32 v247, 31, v91
	v_bfi_b32 v91, v247, v91, v246
	v_xor_b32_e32 v240, 0x7fffffff, v92
	v_ashrrev_i32_e32 v241, 31, v92
	v_bfi_b32 v92, v241, v92, v240
	v_xor_b32_e32 v242, 0x7fffffff, v93
	v_ashrrev_i32_e32 v243, 31, v93
	v_bfi_b32 v93, v243, v93, v242
	v_xor_b32_e32 v244, 0x7fffffff, v94
	v_ashrrev_i32_e32 v245, 31, v94
	v_bfi_b32 v94, v245, v94, v244
	v_xor_b32_e32 v246, 0x7fffffff, v95
	v_ashrrev_i32_e32 v247, 31, v95
	v_bfi_b32 v95, v247, v95, v246
	s_branch .Lsel_cv_next5
.Lsel_cv_slow5:
	v_cmp_lt_i32_e32 vcc, 0x1400, v138
	v_xor_b32_e32 v240, 0x7fffffff, v80
	v_ashrrev_i32_e32 v241, 31, v80
	v_bfi_b32 v80, v241, v80, v240
	v_cndmask_b32_e32 v80, -1, v80, vcc
	v_cmp_lt_i32_e32 vcc, 0x1440, v138
	v_xor_b32_e32 v242, 0x7fffffff, v81
	v_ashrrev_i32_e32 v243, 31, v81
	v_bfi_b32 v81, v243, v81, v242
	v_cndmask_b32_e32 v81, -1, v81, vcc
	v_cmp_lt_i32_e32 vcc, 0x1480, v138
	v_xor_b32_e32 v244, 0x7fffffff, v82
	v_ashrrev_i32_e32 v245, 31, v82
	v_bfi_b32 v82, v245, v82, v244
	v_cndmask_b32_e32 v82, -1, v82, vcc
	v_cmp_lt_i32_e32 vcc, 0x14c0, v138
	v_xor_b32_e32 v246, 0x7fffffff, v83
	v_ashrrev_i32_e32 v247, 31, v83
	v_bfi_b32 v83, v247, v83, v246
	v_cndmask_b32_e32 v83, -1, v83, vcc
	v_cmp_lt_i32_e32 vcc, 0x1500, v138
	v_xor_b32_e32 v240, 0x7fffffff, v84
	v_ashrrev_i32_e32 v241, 31, v84
	v_bfi_b32 v84, v241, v84, v240
	v_cndmask_b32_e32 v84, -1, v84, vcc
	v_cmp_lt_i32_e32 vcc, 0x1540, v138
	v_xor_b32_e32 v242, 0x7fffffff, v85
	v_ashrrev_i32_e32 v243, 31, v85
	v_bfi_b32 v85, v243, v85, v242
	v_cndmask_b32_e32 v85, -1, v85, vcc
	v_cmp_lt_i32_e32 vcc, 0x1580, v138
	v_xor_b32_e32 v244, 0x7fffffff, v86
	v_ashrrev_i32_e32 v245, 31, v86
	v_bfi_b32 v86, v245, v86, v244
	v_cndmask_b32_e32 v86, -1, v86, vcc
	v_cmp_lt_i32_e32 vcc, 0x15c0, v138
	v_xor_b32_e32 v246, 0x7fffffff, v87
	v_ashrrev_i32_e32 v247, 31, v87
	v_bfi_b32 v87, v247, v87, v246
	v_cndmask_b32_e32 v87, -1, v87, vcc
	v_cmp_lt_i32_e32 vcc, 0x1600, v138
	v_xor_b32_e32 v240, 0x7fffffff, v88
	v_ashrrev_i32_e32 v241, 31, v88
	v_bfi_b32 v88, v241, v88, v240
	v_cndmask_b32_e32 v88, -1, v88, vcc
	v_cmp_lt_i32_e32 vcc, 0x1640, v138
	v_xor_b32_e32 v242, 0x7fffffff, v89
	v_ashrrev_i32_e32 v243, 31, v89
	v_bfi_b32 v89, v243, v89, v242
	v_cndmask_b32_e32 v89, -1, v89, vcc
	v_cmp_lt_i32_e32 vcc, 0x1680, v138
	v_xor_b32_e32 v244, 0x7fffffff, v90
	v_ashrrev_i32_e32 v245, 31, v90
	v_bfi_b32 v90, v245, v90, v244
	v_cndmask_b32_e32 v90, -1, v90, vcc
	v_cmp_lt_i32_e32 vcc, 0x16c0, v138
	v_xor_b32_e32 v246, 0x7fffffff, v91
	v_ashrrev_i32_e32 v247, 31, v91
	v_bfi_b32 v91, v247, v91, v246
	v_cndmask_b32_e32 v91, -1, v91, vcc
	v_cmp_lt_i32_e32 vcc, 0x1700, v138
	v_xor_b32_e32 v240, 0x7fffffff, v92
	v_ashrrev_i32_e32 v241, 31, v92
	v_bfi_b32 v92, v241, v92, v240
	v_cndmask_b32_e32 v92, -1, v92, vcc
	v_cmp_lt_i32_e32 vcc, 0x1740, v138
	v_xor_b32_e32 v242, 0x7fffffff, v93
	v_ashrrev_i32_e32 v243, 31, v93
	v_bfi_b32 v93, v243, v93, v242
	v_cndmask_b32_e32 v93, -1, v93, vcc
	v_cmp_lt_i32_e32 vcc, 0x1780, v138
	v_xor_b32_e32 v244, 0x7fffffff, v94
	v_ashrrev_i32_e32 v245, 31, v94
	v_bfi_b32 v94, v245, v94, v244
	v_cndmask_b32_e32 v94, -1, v94, vcc
	v_cmp_lt_i32_e32 vcc, 0x17c0, v138
	v_xor_b32_e32 v246, 0x7fffffff, v95
	v_ashrrev_i32_e32 v247, 31, v95
	v_bfi_b32 v95, v247, v95, v246
	v_cndmask_b32_e32 v95, -1, v95, vcc
.Lsel_cv_next5:
	s_cmpk_le_u32 s34, 96
	s_cbranch_scc1 .Lsel_cv_done
	s_cmpk_ge_u32 s33, 7168
	s_cbranch_scc0 .Lsel_cv_slow6
	v_xor_b32_e32 v240, 0x7fffffff, v208
	v_ashrrev_i32_e32 v241, 31, v208
	v_bfi_b32 v208, v241, v208, v240
	v_xor_b32_e32 v242, 0x7fffffff, v209
	v_ashrrev_i32_e32 v243, 31, v209
	v_bfi_b32 v209, v243, v209, v242
	v_xor_b32_e32 v244, 0x7fffffff, v210
	v_ashrrev_i32_e32 v245, 31, v210
	v_bfi_b32 v210, v245, v210, v244
	v_xor_b32_e32 v246, 0x7fffffff, v211
	v_ashrrev_i32_e32 v247, 31, v211
	v_bfi_b32 v211, v247, v211, v246
	v_xor_b32_e32 v240, 0x7fffffff, v212
	v_ashrrev_i32_e32 v241, 31, v212
	v_bfi_b32 v212, v241, v212, v240
	v_xor_b32_e32 v242, 0x7fffffff, v213
	v_ashrrev_i32_e32 v243, 31, v213
	v_bfi_b32 v213, v243, v213, v242
	v_xor_b32_e32 v244, 0x7fffffff, v214
	v_ashrrev_i32_e32 v245, 31, v214
	v_bfi_b32 v214, v245, v214, v244
	v_xor_b32_e32 v246, 0x7fffffff, v215
	v_ashrrev_i32_e32 v247, 31, v215
	v_bfi_b32 v215, v247, v215, v246
	v_xor_b32_e32 v240, 0x7fffffff, v216
	v_ashrrev_i32_e32 v241, 31, v216
	v_bfi_b32 v216, v241, v216, v240
	v_xor_b32_e32 v242, 0x7fffffff, v217
	v_ashrrev_i32_e32 v243, 31, v217
	v_bfi_b32 v217, v243, v217, v242
	v_xor_b32_e32 v244, 0x7fffffff, v218
	v_ashrrev_i32_e32 v245, 31, v218
	v_bfi_b32 v218, v245, v218, v244
	v_xor_b32_e32 v246, 0x7fffffff, v219
	v_ashrrev_i32_e32 v247, 31, v219
	v_bfi_b32 v219, v247, v219, v246
	v_xor_b32_e32 v240, 0x7fffffff, v220
	v_ashrrev_i32_e32 v241, 31, v220
	v_bfi_b32 v220, v241, v220, v240
	v_xor_b32_e32 v242, 0x7fffffff, v221
	v_ashrrev_i32_e32 v243, 31, v221
	v_bfi_b32 v221, v243, v221, v242
	v_xor_b32_e32 v244, 0x7fffffff, v222
	v_ashrrev_i32_e32 v245, 31, v222
	v_bfi_b32 v222, v245, v222, v244
	v_xor_b32_e32 v246, 0x7fffffff, v223
	v_ashrrev_i32_e32 v247, 31, v223
	v_bfi_b32 v223, v247, v223, v246
	s_branch .Lsel_cv_next6
.Lsel_cv_slow6:
	v_cmp_lt_i32_e32 vcc, 0x1800, v138
	v_xor_b32_e32 v240, 0x7fffffff, v208
	v_ashrrev_i32_e32 v241, 31, v208
	v_bfi_b32 v208, v241, v208, v240
	v_cndmask_b32_e32 v208, -1, v208, vcc
	v_cmp_lt_i32_e32 vcc, 0x1840, v138
	v_xor_b32_e32 v242, 0x7fffffff, v209
	v_ashrrev_i32_e32 v243, 31, v209
	v_bfi_b32 v209, v243, v209, v242
	v_cndmask_b32_e32 v209, -1, v209, vcc
	v_cmp_lt_i32_e32 vcc, 0x1880, v138
	v_xor_b32_e32 v244, 0x7fffffff, v210
	v_ashrrev_i32_e32 v245, 31, v210
	v_bfi_b32 v210, v245, v210, v244
	v_cndmask_b32_e32 v210, -1, v210, vcc
	v_cmp_lt_i32_e32 vcc, 0x18c0, v138
	v_xor_b32_e32 v246, 0x7fffffff, v211
	v_ashrrev_i32_e32 v247, 31, v211
	v_bfi_b32 v211, v247, v211, v246
	v_cndmask_b32_e32 v211, -1, v211, vcc
	v_cmp_lt_i32_e32 vcc, 0x1900, v138
	v_xor_b32_e32 v240, 0x7fffffff, v212
	v_ashrrev_i32_e32 v241, 31, v212
	v_bfi_b32 v212, v241, v212, v240
	v_cndmask_b32_e32 v212, -1, v212, vcc
	v_cmp_lt_i32_e32 vcc, 0x1940, v138
	v_xor_b32_e32 v242, 0x7fffffff, v213
	v_ashrrev_i32_e32 v243, 31, v213
	v_bfi_b32 v213, v243, v213, v242
	v_cndmask_b32_e32 v213, -1, v213, vcc
	v_cmp_lt_i32_e32 vcc, 0x1980, v138
	v_xor_b32_e32 v244, 0x7fffffff, v214
	v_ashrrev_i32_e32 v245, 31, v214
	v_bfi_b32 v214, v245, v214, v244
	v_cndmask_b32_e32 v214, -1, v214, vcc
	v_cmp_lt_i32_e32 vcc, 0x19c0, v138
	v_xor_b32_e32 v246, 0x7fffffff, v215
	v_ashrrev_i32_e32 v247, 31, v215
	v_bfi_b32 v215, v247, v215, v246
	v_cndmask_b32_e32 v215, -1, v215, vcc
	v_cmp_lt_i32_e32 vcc, 0x1a00, v138
	v_xor_b32_e32 v240, 0x7fffffff, v216
	v_ashrrev_i32_e32 v241, 31, v216
	v_bfi_b32 v216, v241, v216, v240
	v_cndmask_b32_e32 v216, -1, v216, vcc
	v_cmp_lt_i32_e32 vcc, 0x1a40, v138
	v_xor_b32_e32 v242, 0x7fffffff, v217
	v_ashrrev_i32_e32 v243, 31, v217
	v_bfi_b32 v217, v243, v217, v242
	v_cndmask_b32_e32 v217, -1, v217, vcc
	v_cmp_lt_i32_e32 vcc, 0x1a80, v138
	v_xor_b32_e32 v244, 0x7fffffff, v218
	v_ashrrev_i32_e32 v245, 31, v218
	v_bfi_b32 v218, v245, v218, v244
	v_cndmask_b32_e32 v218, -1, v218, vcc
	v_cmp_lt_i32_e32 vcc, 0x1ac0, v138
	v_xor_b32_e32 v246, 0x7fffffff, v219
	v_ashrrev_i32_e32 v247, 31, v219
	v_bfi_b32 v219, v247, v219, v246
	v_cndmask_b32_e32 v219, -1, v219, vcc
	v_cmp_lt_i32_e32 vcc, 0x1b00, v138
	v_xor_b32_e32 v240, 0x7fffffff, v220
	v_ashrrev_i32_e32 v241, 31, v220
	v_bfi_b32 v220, v241, v220, v240
	v_cndmask_b32_e32 v220, -1, v220, vcc
	v_cmp_lt_i32_e32 vcc, 0x1b40, v138
	v_xor_b32_e32 v242, 0x7fffffff, v221
	v_ashrrev_i32_e32 v243, 31, v221
	v_bfi_b32 v221, v243, v221, v242
	v_cndmask_b32_e32 v221, -1, v221, vcc
	v_cmp_lt_i32_e32 vcc, 0x1b80, v138
	v_xor_b32_e32 v244, 0x7fffffff, v222
	v_ashrrev_i32_e32 v245, 31, v222
	v_bfi_b32 v222, v245, v222, v244
	v_cndmask_b32_e32 v222, -1, v222, vcc
	v_cmp_lt_i32_e32 vcc, 0x1bc0, v138
	v_xor_b32_e32 v246, 0x7fffffff, v223
	v_ashrrev_i32_e32 v247, 31, v223
	v_bfi_b32 v223, v247, v223, v246
	v_cndmask_b32_e32 v223, -1, v223, vcc
.Lsel_cv_next6:
	s_cmpk_le_u32 s34, 112
	s_cbranch_scc1 .Lsel_cv_done
	s_cmpk_ge_u32 s33, 8192
	s_cbranch_scc0 .Lsel_cv_slow7
	v_xor_b32_e32 v240, 0x7fffffff, v224
	v_ashrrev_i32_e32 v241, 31, v224
	v_bfi_b32 v224, v241, v224, v240
	v_xor_b32_e32 v242, 0x7fffffff, v225
	v_ashrrev_i32_e32 v243, 31, v225
	v_bfi_b32 v225, v243, v225, v242
	v_xor_b32_e32 v244, 0x7fffffff, v226
	v_ashrrev_i32_e32 v245, 31, v226
	v_bfi_b32 v226, v245, v226, v244
	v_xor_b32_e32 v246, 0x7fffffff, v227
	v_ashrrev_i32_e32 v247, 31, v227
	v_bfi_b32 v227, v247, v227, v246
	v_xor_b32_e32 v240, 0x7fffffff, v228
	v_ashrrev_i32_e32 v241, 31, v228
	v_bfi_b32 v228, v241, v228, v240
	v_xor_b32_e32 v242, 0x7fffffff, v229
	v_ashrrev_i32_e32 v243, 31, v229
	v_bfi_b32 v229, v243, v229, v242
	v_xor_b32_e32 v244, 0x7fffffff, v230
	v_ashrrev_i32_e32 v245, 31, v230
	v_bfi_b32 v230, v245, v230, v244
	v_xor_b32_e32 v246, 0x7fffffff, v231
	v_ashrrev_i32_e32 v247, 31, v231
	v_bfi_b32 v231, v247, v231, v246
	v_xor_b32_e32 v240, 0x7fffffff, v232
	v_ashrrev_i32_e32 v241, 31, v232
	v_bfi_b32 v232, v241, v232, v240
	v_xor_b32_e32 v242, 0x7fffffff, v233
	v_ashrrev_i32_e32 v243, 31, v233
	v_bfi_b32 v233, v243, v233, v242
	v_xor_b32_e32 v244, 0x7fffffff, v234
	v_ashrrev_i32_e32 v245, 31, v234
	v_bfi_b32 v234, v245, v234, v244
	v_xor_b32_e32 v246, 0x7fffffff, v235
	v_ashrrev_i32_e32 v247, 31, v235
	v_bfi_b32 v235, v247, v235, v246
	v_xor_b32_e32 v240, 0x7fffffff, v236
	v_ashrrev_i32_e32 v241, 31, v236
	v_bfi_b32 v236, v241, v236, v240
	v_xor_b32_e32 v242, 0x7fffffff, v237
	v_ashrrev_i32_e32 v243, 31, v237
	v_bfi_b32 v237, v243, v237, v242
	v_xor_b32_e32 v244, 0x7fffffff, v238
	v_ashrrev_i32_e32 v245, 31, v238
	v_bfi_b32 v238, v245, v238, v244
	v_xor_b32_e32 v246, 0x7fffffff, v239
	v_ashrrev_i32_e32 v247, 31, v239
	v_bfi_b32 v239, v247, v239, v246
	s_branch .Lsel_cv_next7
.Lsel_cv_slow7:
	v_cmp_lt_i32_e32 vcc, 0x1c00, v138
	v_xor_b32_e32 v240, 0x7fffffff, v224
	v_ashrrev_i32_e32 v241, 31, v224
	v_bfi_b32 v224, v241, v224, v240
	v_cndmask_b32_e32 v224, -1, v224, vcc
	v_cmp_lt_i32_e32 vcc, 0x1c40, v138
	v_xor_b32_e32 v242, 0x7fffffff, v225
	v_ashrrev_i32_e32 v243, 31, v225
	v_bfi_b32 v225, v243, v225, v242
	v_cndmask_b32_e32 v225, -1, v225, vcc
	v_cmp_lt_i32_e32 vcc, 0x1c80, v138
	v_xor_b32_e32 v244, 0x7fffffff, v226
	v_ashrrev_i32_e32 v245, 31, v226
	v_bfi_b32 v226, v245, v226, v244
	v_cndmask_b32_e32 v226, -1, v226, vcc
	v_cmp_lt_i32_e32 vcc, 0x1cc0, v138
	v_xor_b32_e32 v246, 0x7fffffff, v227
	v_ashrrev_i32_e32 v247, 31, v227
	v_bfi_b32 v227, v247, v227, v246
	v_cndmask_b32_e32 v227, -1, v227, vcc
	v_cmp_lt_i32_e32 vcc, 0x1d00, v138
	v_xor_b32_e32 v240, 0x7fffffff, v228
	v_ashrrev_i32_e32 v241, 31, v228
	v_bfi_b32 v228, v241, v228, v240
	v_cndmask_b32_e32 v228, -1, v228, vcc
	v_cmp_lt_i32_e32 vcc, 0x1d40, v138
	v_xor_b32_e32 v242, 0x7fffffff, v229
	v_ashrrev_i32_e32 v243, 31, v229
	v_bfi_b32 v229, v243, v229, v242
	v_cndmask_b32_e32 v229, -1, v229, vcc
	v_cmp_lt_i32_e32 vcc, 0x1d80, v138
	v_xor_b32_e32 v244, 0x7fffffff, v230
	v_ashrrev_i32_e32 v245, 31, v230
	v_bfi_b32 v230, v245, v230, v244
	v_cndmask_b32_e32 v230, -1, v230, vcc
	v_cmp_lt_i32_e32 vcc, 0x1dc0, v138
	v_xor_b32_e32 v246, 0x7fffffff, v231
	v_ashrrev_i32_e32 v247, 31, v231
	v_bfi_b32 v231, v247, v231, v246
	v_cndmask_b32_e32 v231, -1, v231, vcc
	v_cmp_lt_i32_e32 vcc, 0x1e00, v138
	v_xor_b32_e32 v240, 0x7fffffff, v232
	v_ashrrev_i32_e32 v241, 31, v232
	v_bfi_b32 v232, v241, v232, v240
	v_cndmask_b32_e32 v232, -1, v232, vcc
	v_cmp_lt_i32_e32 vcc, 0x1e40, v138
	v_xor_b32_e32 v242, 0x7fffffff, v233
	v_ashrrev_i32_e32 v243, 31, v233
	v_bfi_b32 v233, v243, v233, v242
	v_cndmask_b32_e32 v233, -1, v233, vcc
	v_cmp_lt_i32_e32 vcc, 0x1e80, v138
	v_xor_b32_e32 v244, 0x7fffffff, v234
	v_ashrrev_i32_e32 v245, 31, v234
	v_bfi_b32 v234, v245, v234, v244
	v_cndmask_b32_e32 v234, -1, v234, vcc
	v_cmp_lt_i32_e32 vcc, 0x1ec0, v138
	v_xor_b32_e32 v246, 0x7fffffff, v235
	v_ashrrev_i32_e32 v247, 31, v235
	v_bfi_b32 v235, v247, v235, v246
	v_cndmask_b32_e32 v235, -1, v235, vcc
	v_cmp_lt_i32_e32 vcc, 0x1f00, v138
	v_xor_b32_e32 v240, 0x7fffffff, v236
	v_ashrrev_i32_e32 v241, 31, v236
	v_bfi_b32 v236, v241, v236, v240
	v_cndmask_b32_e32 v236, -1, v236, vcc
	v_cmp_lt_i32_e32 vcc, 0x1f40, v138
	v_xor_b32_e32 v242, 0x7fffffff, v237
	v_ashrrev_i32_e32 v243, 31, v237
	v_bfi_b32 v237, v243, v237, v242
	v_cndmask_b32_e32 v237, -1, v237, vcc
	v_cmp_lt_i32_e32 vcc, 0x1f80, v138
	v_xor_b32_e32 v244, 0x7fffffff, v238
	v_ashrrev_i32_e32 v245, 31, v238
	v_bfi_b32 v238, v245, v238, v244
	v_cndmask_b32_e32 v238, -1, v238, vcc
	v_cmp_lt_i32_e32 vcc, 0x1fc0, v138
	v_xor_b32_e32 v246, 0x7fffffff, v239
	v_ashrrev_i32_e32 v247, 31, v239
	v_bfi_b32 v239, v247, v239, v246
	v_cndmask_b32_e32 v239, -1, v239, vcc
.Lsel_cv_next7:
.Lsel_cv_done:
	s_movk_i32 s56, 0x100
	s_mov_b32 s57, 0
	s_mov_b32 s86, -1
	s_mov_b32 s87, 21
	s_mov_b32 s88, 0
.Lsel_pass:
	v_mov_b32_e32 v240, 0
	v_mov_b32_e32 v241, 0
	v_mov_b32_e32 v242, 0
	v_mov_b32_e32 v243, 0
	v_lshl_add_u32 v140, v131, 4, v136
	ds_write_b128 v140, v[240:243]
	ds_write_b128 v140, v[240:243] offset:1024
	ds_write_b128 v140, v[240:243] offset:2048
	ds_write_b128 v140, v[240:243] offset:3072
	ds_write_b128 v140, v[240:243] offset:4096
	ds_write_b128 v140, v[240:243] offset:5120
	ds_write_b128 v140, v[240:243] offset:6144
	ds_write_b128 v140, v[240:243] offset:7168
	s_waitcnt lgkmcnt(0)
	v_xor_b32_e32 v240, s57, v0
	v_cmp_lt_u32_e64 s[52:53], v240, s86
	v_lshrrev_b32_e32 v241, s87, v240
	v_lshl_add_u32 v241, v241, 2, v136
	v_cndmask_b32_e64 v241, v137, v241, s[52:53]
	ds_add_u32 v241, v135
	v_xor_b32_e32 v242, s57, v1
	v_cmp_lt_u32_e64 s[52:53], v242, s86
	v_lshrrev_b32_e32 v243, s87, v242
	v_lshl_add_u32 v243, v243, 2, v136
	v_cndmask_b32_e64 v243, v137, v243, s[52:53]
	ds_add_u32 v243, v135
	v_xor_b32_e32 v244, s57, v2
	v_cmp_lt_u32_e64 s[52:53], v244, s86
	v_lshrrev_b32_e32 v245, s87, v244
	v_lshl_add_u32 v245, v245, 2, v136
	v_cndmask_b32_e64 v245, v137, v245, s[52:53]
	ds_add_u32 v245, v135
	v_xor_b32_e32 v246, s57, v3
	v_cmp_lt_u32_e64 s[52:53], v246, s86
	v_lshrrev_b32_e32 v247, s87, v246
	v_lshl_add_u32 v247, v247, 2, v136
	v_cndmask_b32_e64 v247, v137, v247, s[52:53]
	ds_add_u32 v247, v135
	v_xor_b32_e32 v240, s57, v4
	v_cmp_lt_u32_e64 s[52:53], v240, s86
	v_lshrrev_b32_e32 v241, s87, v240
	v_lshl_add_u32 v241, v241, 2, v136
	v_cndmask_b32_e64 v241, v137, v241, s[52:53]
	ds_add_u32 v241, v135
	v_xor_b32_e32 v242, s57, v5
	v_cmp_lt_u32_e64 s[52:53], v242, s86
	v_lshrrev_b32_e32 v243, s87, v242
	v_lshl_add_u32 v243, v243, 2, v136
	v_cndmask_b32_e64 v243, v137, v243, s[52:53]
	ds_add_u32 v243, v135
	v_xor_b32_e32 v244, s57, v6
	v_cmp_lt_u32_e64 s[52:53], v244, s86
	v_lshrrev_b32_e32 v245, s87, v244
	v_lshl_add_u32 v245, v245, 2, v136
	v_cndmask_b32_e64 v245, v137, v245, s[52:53]
	ds_add_u32 v245, v135
	v_xor_b32_e32 v246, s57, v7
	v_cmp_lt_u32_e64 s[52:53], v246, s86
	v_lshrrev_b32_e32 v247, s87, v246
	v_lshl_add_u32 v247, v247, 2, v136
	v_cndmask_b32_e64 v247, v137, v247, s[52:53]
	ds_add_u32 v247, v135
	v_xor_b32_e32 v240, s57, v8
	v_cmp_lt_u32_e64 s[52:53], v240, s86
	v_lshrrev_b32_e32 v241, s87, v240
	v_lshl_add_u32 v241, v241, 2, v136
	v_cndmask_b32_e64 v241, v137, v241, s[52:53]
	ds_add_u32 v241, v135
	v_xor_b32_e32 v242, s57, v9
	v_cmp_lt_u32_e64 s[52:53], v242, s86
	v_lshrrev_b32_e32 v243, s87, v242
	v_lshl_add_u32 v243, v243, 2, v136
	v_cndmask_b32_e64 v243, v137, v243, s[52:53]
	ds_add_u32 v243, v135
	v_xor_b32_e32 v244, s57, v10
	v_cmp_lt_u32_e64 s[52:53], v244, s86
	v_lshrrev_b32_e32 v245, s87, v244
	v_lshl_add_u32 v245, v245, 2, v136
	v_cndmask_b32_e64 v245, v137, v245, s[52:53]
	ds_add_u32 v245, v135
	v_xor_b32_e32 v246, s57, v11
	v_cmp_lt_u32_e64 s[52:53], v246, s86
	v_lshrrev_b32_e32 v247, s87, v246
	v_lshl_add_u32 v247, v247, 2, v136
	v_cndmask_b32_e64 v247, v137, v247, s[52:53]
	ds_add_u32 v247, v135
	v_xor_b32_e32 v240, s57, v12
	v_cmp_lt_u32_e64 s[52:53], v240, s86
	v_lshrrev_b32_e32 v241, s87, v240
	v_lshl_add_u32 v241, v241, 2, v136
	v_cndmask_b32_e64 v241, v137, v241, s[52:53]
	ds_add_u32 v241, v135
	v_xor_b32_e32 v242, s57, v13
	v_cmp_lt_u32_e64 s[52:53], v242, s86
	v_lshrrev_b32_e32 v243, s87, v242
	v_lshl_add_u32 v243, v243, 2, v136
	v_cndmask_b32_e64 v243, v137, v243, s[52:53]
	ds_add_u32 v243, v135
	v_xor_b32_e32 v244, s57, v14
	v_cmp_lt_u32_e64 s[52:53], v244, s86
	v_lshrrev_b32_e32 v245, s87, v244
	v_lshl_add_u32 v245, v245, 2, v136
	v_cndmask_b32_e64 v245, v137, v245, s[52:53]
	ds_add_u32 v245, v135
	v_xor_b32_e32 v246, s57, v15
	v_cmp_lt_u32_e64 s[52:53], v246, s86
	v_lshrrev_b32_e32 v247, s87, v246
	v_lshl_add_u32 v247, v247, 2, v136
	v_cndmask_b32_e64 v247, v137, v247, s[52:53]
	ds_add_u32 v247, v135
	s_cmpk_le_u32 s34, 16
	s_cbranch_scc1 .Lsel_hist_done
	v_xor_b32_e32 v240, s57, v16
	v_cmp_lt_u32_e64 s[52:53], v240, s86
	v_lshrrev_b32_e32 v241, s87, v240
	v_lshl_add_u32 v241, v241, 2, v136
	v_cndmask_b32_e64 v241, v137, v241, s[52:53]
	ds_add_u32 v241, v135
	v_xor_b32_e32 v242, s57, v17
	v_cmp_lt_u32_e64 s[52:53], v242, s86
	v_lshrrev_b32_e32 v243, s87, v242
	v_lshl_add_u32 v243, v243, 2, v136
	v_cndmask_b32_e64 v243, v137, v243, s[52:53]
	ds_add_u32 v243, v135
	v_xor_b32_e32 v244, s57, v18
	v_cmp_lt_u32_e64 s[52:53], v244, s86
	v_lshrrev_b32_e32 v245, s87, v244
	v_lshl_add_u32 v245, v245, 2, v136
	v_cndmask_b32_e64 v245, v137, v245, s[52:53]
	ds_add_u32 v245, v135
	v_xor_b32_e32 v246, s57, v19
	v_cmp_lt_u32_e64 s[52:53], v246, s86
	v_lshrrev_b32_e32 v247, s87, v246
	v_lshl_add_u32 v247, v247, 2, v136
	v_cndmask_b32_e64 v247, v137, v247, s[52:53]
	ds_add_u32 v247, v135
	v_xor_b32_e32 v240, s57, v20
	v_cmp_lt_u32_e64 s[52:53], v240, s86
	v_lshrrev_b32_e32 v241, s87, v240
	v_lshl_add_u32 v241, v241, 2, v136
	v_cndmask_b32_e64 v241, v137, v241, s[52:53]
	ds_add_u32 v241, v135
	v_xor_b32_e32 v242, s57, v21
	v_cmp_lt_u32_e64 s[52:53], v242, s86
	v_lshrrev_b32_e32 v243, s87, v242
	v_lshl_add_u32 v243, v243, 2, v136
	v_cndmask_b32_e64 v243, v137, v243, s[52:53]
	ds_add_u32 v243, v135
	v_xor_b32_e32 v244, s57, v22
	v_cmp_lt_u32_e64 s[52:53], v244, s86
	v_lshrrev_b32_e32 v245, s87, v244
	v_lshl_add_u32 v245, v245, 2, v136
	v_cndmask_b32_e64 v245, v137, v245, s[52:53]
	ds_add_u32 v245, v135
	v_xor_b32_e32 v246, s57, v23
	v_cmp_lt_u32_e64 s[52:53], v246, s86
	v_lshrrev_b32_e32 v247, s87, v246
	v_lshl_add_u32 v247, v247, 2, v136
	v_cndmask_b32_e64 v247, v137, v247, s[52:53]
	ds_add_u32 v247, v135
	v_xor_b32_e32 v240, s57, v24
	v_cmp_lt_u32_e64 s[52:53], v240, s86
	v_lshrrev_b32_e32 v241, s87, v240
	v_lshl_add_u32 v241, v241, 2, v136
	v_cndmask_b32_e64 v241, v137, v241, s[52:53]
	ds_add_u32 v241, v135
	v_xor_b32_e32 v242, s57, v25
	v_cmp_lt_u32_e64 s[52:53], v242, s86
	v_lshrrev_b32_e32 v243, s87, v242
	v_lshl_add_u32 v243, v243, 2, v136
	v_cndmask_b32_e64 v243, v137, v243, s[52:53]
	ds_add_u32 v243, v135
	v_xor_b32_e32 v244, s57, v26
	v_cmp_lt_u32_e64 s[52:53], v244, s86
	v_lshrrev_b32_e32 v245, s87, v244
	v_lshl_add_u32 v245, v245, 2, v136
	v_cndmask_b32_e64 v245, v137, v245, s[52:53]
	ds_add_u32 v245, v135
	v_xor_b32_e32 v246, s57, v27
	v_cmp_lt_u32_e64 s[52:53], v246, s86
	v_lshrrev_b32_e32 v247, s87, v246
	v_lshl_add_u32 v247, v247, 2, v136
	v_cndmask_b32_e64 v247, v137, v247, s[52:53]
	ds_add_u32 v247, v135
	v_xor_b32_e32 v240, s57, v28
	v_cmp_lt_u32_e64 s[52:53], v240, s86
	v_lshrrev_b32_e32 v241, s87, v240
	v_lshl_add_u32 v241, v241, 2, v136
	v_cndmask_b32_e64 v241, v137, v241, s[52:53]
	ds_add_u32 v241, v135
	v_xor_b32_e32 v242, s57, v29
	v_cmp_lt_u32_e64 s[52:53], v242, s86
	v_lshrrev_b32_e32 v243, s87, v242
	v_lshl_add_u32 v243, v243, 2, v136
	v_cndmask_b32_e64 v243, v137, v243, s[52:53]
	ds_add_u32 v243, v135
	v_xor_b32_e32 v244, s57, v30
	v_cmp_lt_u32_e64 s[52:53], v244, s86
	v_lshrrev_b32_e32 v245, s87, v244
	v_lshl_add_u32 v245, v245, 2, v136
	v_cndmask_b32_e64 v245, v137, v245, s[52:53]
	ds_add_u32 v245, v135
	v_xor_b32_e32 v246, s57, v31
	v_cmp_lt_u32_e64 s[52:53], v246, s86
	v_lshrrev_b32_e32 v247, s87, v246
	v_lshl_add_u32 v247, v247, 2, v136
	v_cndmask_b32_e64 v247, v137, v247, s[52:53]
	ds_add_u32 v247, v135
	s_cmpk_le_u32 s34, 32
	s_cbranch_scc1 .Lsel_hist_done
	v_xor_b32_e32 v240, s57, v32
	v_cmp_lt_u32_e64 s[52:53], v240, s86
	v_lshrrev_b32_e32 v241, s87, v240
	v_lshl_add_u32 v241, v241, 2, v136
	v_cndmask_b32_e64 v241, v137, v241, s[52:53]
	ds_add_u32 v241, v135
	v_xor_b32_e32 v242, s57, v33
	v_cmp_lt_u32_e64 s[52:53], v242, s86
	v_lshrrev_b32_e32 v243, s87, v242
	v_lshl_add_u32 v243, v243, 2, v136
	v_cndmask_b32_e64 v243, v137, v243, s[52:53]
	ds_add_u32 v243, v135
	v_xor_b32_e32 v244, s57, v34
	v_cmp_lt_u32_e64 s[52:53], v244, s86
	v_lshrrev_b32_e32 v245, s87, v244
	v_lshl_add_u32 v245, v245, 2, v136
	v_cndmask_b32_e64 v245, v137, v245, s[52:53]
	ds_add_u32 v245, v135
	v_xor_b32_e32 v246, s57, v35
	v_cmp_lt_u32_e64 s[52:53], v246, s86
	v_lshrrev_b32_e32 v247, s87, v246
	v_lshl_add_u32 v247, v247, 2, v136
	v_cndmask_b32_e64 v247, v137, v247, s[52:53]
	ds_add_u32 v247, v135
	v_xor_b32_e32 v240, s57, v36
	v_cmp_lt_u32_e64 s[52:53], v240, s86
	v_lshrrev_b32_e32 v241, s87, v240
	v_lshl_add_u32 v241, v241, 2, v136
	v_cndmask_b32_e64 v241, v137, v241, s[52:53]
	ds_add_u32 v241, v135
	v_xor_b32_e32 v242, s57, v37
	v_cmp_lt_u32_e64 s[52:53], v242, s86
	v_lshrrev_b32_e32 v243, s87, v242
	v_lshl_add_u32 v243, v243, 2, v136
	v_cndmask_b32_e64 v243, v137, v243, s[52:53]
	ds_add_u32 v243, v135
	v_xor_b32_e32 v244, s57, v38
	v_cmp_lt_u32_e64 s[52:53], v244, s86
	v_lshrrev_b32_e32 v245, s87, v244
	v_lshl_add_u32 v245, v245, 2, v136
	v_cndmask_b32_e64 v245, v137, v245, s[52:53]
	ds_add_u32 v245, v135
	v_xor_b32_e32 v246, s57, v39
	v_cmp_lt_u32_e64 s[52:53], v246, s86
	v_lshrrev_b32_e32 v247, s87, v246
	v_lshl_add_u32 v247, v247, 2, v136
	v_cndmask_b32_e64 v247, v137, v247, s[52:53]
	ds_add_u32 v247, v135
	v_xor_b32_e32 v240, s57, v40
	v_cmp_lt_u32_e64 s[52:53], v240, s86
	v_lshrrev_b32_e32 v241, s87, v240
	v_lshl_add_u32 v241, v241, 2, v136
	v_cndmask_b32_e64 v241, v137, v241, s[52:53]
	ds_add_u32 v241, v135
	v_xor_b32_e32 v242, s57, v41
	v_cmp_lt_u32_e64 s[52:53], v242, s86
	v_lshrrev_b32_e32 v243, s87, v242
	v_lshl_add_u32 v243, v243, 2, v136
	v_cndmask_b32_e64 v243, v137, v243, s[52:53]
	ds_add_u32 v243, v135
	v_xor_b32_e32 v244, s57, v42
	v_cmp_lt_u32_e64 s[52:53], v244, s86
	v_lshrrev_b32_e32 v245, s87, v244
	v_lshl_add_u32 v245, v245, 2, v136
	v_cndmask_b32_e64 v245, v137, v245, s[52:53]
	ds_add_u32 v245, v135
	v_xor_b32_e32 v246, s57, v43
	v_cmp_lt_u32_e64 s[52:53], v246, s86
	v_lshrrev_b32_e32 v247, s87, v246
	v_lshl_add_u32 v247, v247, 2, v136
	v_cndmask_b32_e64 v247, v137, v247, s[52:53]
	ds_add_u32 v247, v135
	v_xor_b32_e32 v240, s57, v44
	v_cmp_lt_u32_e64 s[52:53], v240, s86
	v_lshrrev_b32_e32 v241, s87, v240
	v_lshl_add_u32 v241, v241, 2, v136
	v_cndmask_b32_e64 v241, v137, v241, s[52:53]
	ds_add_u32 v241, v135
	v_xor_b32_e32 v242, s57, v45
	v_cmp_lt_u32_e64 s[52:53], v242, s86
	v_lshrrev_b32_e32 v243, s87, v242
	v_lshl_add_u32 v243, v243, 2, v136
	v_cndmask_b32_e64 v243, v137, v243, s[52:53]
	ds_add_u32 v243, v135
	v_xor_b32_e32 v244, s57, v46
	v_cmp_lt_u32_e64 s[52:53], v244, s86
	v_lshrrev_b32_e32 v245, s87, v244
	v_lshl_add_u32 v245, v245, 2, v136
	v_cndmask_b32_e64 v245, v137, v245, s[52:53]
	ds_add_u32 v245, v135
	v_xor_b32_e32 v246, s57, v47
	v_cmp_lt_u32_e64 s[52:53], v246, s86
	v_lshrrev_b32_e32 v247, s87, v246
	v_lshl_add_u32 v247, v247, 2, v136
	v_cndmask_b32_e64 v247, v137, v247, s[52:53]
	ds_add_u32 v247, v135
	s_cmpk_le_u32 s34, 48
	s_cbranch_scc1 .Lsel_hist_done
	v_xor_b32_e32 v240, s57, v48
	v_cmp_lt_u32_e64 s[52:53], v240, s86
	v_lshrrev_b32_e32 v241, s87, v240
	v_lshl_add_u32 v241, v241, 2, v136
	v_cndmask_b32_e64 v241, v137, v241, s[52:53]
	ds_add_u32 v241, v135
	v_xor_b32_e32 v242, s57, v49
	v_cmp_lt_u32_e64 s[52:53], v242, s86
	v_lshrrev_b32_e32 v243, s87, v242
	v_lshl_add_u32 v243, v243, 2, v136
	v_cndmask_b32_e64 v243, v137, v243, s[52:53]
	ds_add_u32 v243, v135
	v_xor_b32_e32 v244, s57, v50
	v_cmp_lt_u32_e64 s[52:53], v244, s86
	v_lshrrev_b32_e32 v245, s87, v244
	v_lshl_add_u32 v245, v245, 2, v136
	v_cndmask_b32_e64 v245, v137, v245, s[52:53]
	ds_add_u32 v245, v135
	v_xor_b32_e32 v246, s57, v51
	v_cmp_lt_u32_e64 s[52:53], v246, s86
	v_lshrrev_b32_e32 v247, s87, v246
	v_lshl_add_u32 v247, v247, 2, v136
	v_cndmask_b32_e64 v247, v137, v247, s[52:53]
	ds_add_u32 v247, v135
	v_xor_b32_e32 v240, s57, v52
	v_cmp_lt_u32_e64 s[52:53], v240, s86
	v_lshrrev_b32_e32 v241, s87, v240
	v_lshl_add_u32 v241, v241, 2, v136
	v_cndmask_b32_e64 v241, v137, v241, s[52:53]
	ds_add_u32 v241, v135
	v_xor_b32_e32 v242, s57, v53
	v_cmp_lt_u32_e64 s[52:53], v242, s86
	v_lshrrev_b32_e32 v243, s87, v242
	v_lshl_add_u32 v243, v243, 2, v136
	v_cndmask_b32_e64 v243, v137, v243, s[52:53]
	ds_add_u32 v243, v135
	v_xor_b32_e32 v244, s57, v54
	v_cmp_lt_u32_e64 s[52:53], v244, s86
	v_lshrrev_b32_e32 v245, s87, v244
	v_lshl_add_u32 v245, v245, 2, v136
	v_cndmask_b32_e64 v245, v137, v245, s[52:53]
	ds_add_u32 v245, v135
	v_xor_b32_e32 v246, s57, v55
	v_cmp_lt_u32_e64 s[52:53], v246, s86
	v_lshrrev_b32_e32 v247, s87, v246
	v_lshl_add_u32 v247, v247, 2, v136
	v_cndmask_b32_e64 v247, v137, v247, s[52:53]
	ds_add_u32 v247, v135
	v_xor_b32_e32 v240, s57, v56
	v_cmp_lt_u32_e64 s[52:53], v240, s86
	v_lshrrev_b32_e32 v241, s87, v240
	v_lshl_add_u32 v241, v241, 2, v136
	v_cndmask_b32_e64 v241, v137, v241, s[52:53]
	ds_add_u32 v241, v135
	v_xor_b32_e32 v242, s57, v57
	v_cmp_lt_u32_e64 s[52:53], v242, s86
	v_lshrrev_b32_e32 v243, s87, v242
	v_lshl_add_u32 v243, v243, 2, v136
	v_cndmask_b32_e64 v243, v137, v243, s[52:53]
	ds_add_u32 v243, v135
	v_xor_b32_e32 v244, s57, v58
	v_cmp_lt_u32_e64 s[52:53], v244, s86
	v_lshrrev_b32_e32 v245, s87, v244
	v_lshl_add_u32 v245, v245, 2, v136
	v_cndmask_b32_e64 v245, v137, v245, s[52:53]
	ds_add_u32 v245, v135
	v_xor_b32_e32 v246, s57, v59
	v_cmp_lt_u32_e64 s[52:53], v246, s86
	v_lshrrev_b32_e32 v247, s87, v246
	v_lshl_add_u32 v247, v247, 2, v136
	v_cndmask_b32_e64 v247, v137, v247, s[52:53]
	ds_add_u32 v247, v135
	v_xor_b32_e32 v240, s57, v60
	v_cmp_lt_u32_e64 s[52:53], v240, s86
	v_lshrrev_b32_e32 v241, s87, v240
	v_lshl_add_u32 v241, v241, 2, v136
	v_cndmask_b32_e64 v241, v137, v241, s[52:53]
	ds_add_u32 v241, v135
	v_xor_b32_e32 v242, s57, v61
	v_cmp_lt_u32_e64 s[52:53], v242, s86
	v_lshrrev_b32_e32 v243, s87, v242
	v_lshl_add_u32 v243, v243, 2, v136
	v_cndmask_b32_e64 v243, v137, v243, s[52:53]
	ds_add_u32 v243, v135
	v_xor_b32_e32 v244, s57, v62
	v_cmp_lt_u32_e64 s[52:53], v244, s86
	v_lshrrev_b32_e32 v245, s87, v244
	v_lshl_add_u32 v245, v245, 2, v136
	v_cndmask_b32_e64 v245, v137, v245, s[52:53]
	ds_add_u32 v245, v135
	v_xor_b32_e32 v246, s57, v63
	v_cmp_lt_u32_e64 s[52:53], v246, s86
	v_lshrrev_b32_e32 v247, s87, v246
	v_lshl_add_u32 v247, v247, 2, v136
	v_cndmask_b32_e64 v247, v137, v247, s[52:53]
	ds_add_u32 v247, v135
	s_cmpk_le_u32 s34, 64
	s_cbranch_scc1 .Lsel_hist_done
	v_xor_b32_e32 v240, s57, v64
	v_cmp_lt_u32_e64 s[52:53], v240, s86
	v_lshrrev_b32_e32 v241, s87, v240
	v_lshl_add_u32 v241, v241, 2, v136
	v_cndmask_b32_e64 v241, v137, v241, s[52:53]
	ds_add_u32 v241, v135
	v_xor_b32_e32 v242, s57, v65
	v_cmp_lt_u32_e64 s[52:53], v242, s86
	v_lshrrev_b32_e32 v243, s87, v242
	v_lshl_add_u32 v243, v243, 2, v136
	v_cndmask_b32_e64 v243, v137, v243, s[52:53]
	ds_add_u32 v243, v135
	v_xor_b32_e32 v244, s57, v66
	v_cmp_lt_u32_e64 s[52:53], v244, s86
	v_lshrrev_b32_e32 v245, s87, v244
	v_lshl_add_u32 v245, v245, 2, v136
	v_cndmask_b32_e64 v245, v137, v245, s[52:53]
	ds_add_u32 v245, v135
	v_xor_b32_e32 v246, s57, v67
	v_cmp_lt_u32_e64 s[52:53], v246, s86
	v_lshrrev_b32_e32 v247, s87, v246
	v_lshl_add_u32 v247, v247, 2, v136
	v_cndmask_b32_e64 v247, v137, v247, s[52:53]
	ds_add_u32 v247, v135
	v_xor_b32_e32 v240, s57, v68
	v_cmp_lt_u32_e64 s[52:53], v240, s86
	v_lshrrev_b32_e32 v241, s87, v240
	v_lshl_add_u32 v241, v241, 2, v136
	v_cndmask_b32_e64 v241, v137, v241, s[52:53]
	ds_add_u32 v241, v135
	v_xor_b32_e32 v242, s57, v69
	v_cmp_lt_u32_e64 s[52:53], v242, s86
	v_lshrrev_b32_e32 v243, s87, v242
	v_lshl_add_u32 v243, v243, 2, v136
	v_cndmask_b32_e64 v243, v137, v243, s[52:53]
	ds_add_u32 v243, v135
	v_xor_b32_e32 v244, s57, v70
	v_cmp_lt_u32_e64 s[52:53], v244, s86
	v_lshrrev_b32_e32 v245, s87, v244
	v_lshl_add_u32 v245, v245, 2, v136
	v_cndmask_b32_e64 v245, v137, v245, s[52:53]
	ds_add_u32 v245, v135
	v_xor_b32_e32 v246, s57, v71
	v_cmp_lt_u32_e64 s[52:53], v246, s86
	v_lshrrev_b32_e32 v247, s87, v246
	v_lshl_add_u32 v247, v247, 2, v136
	v_cndmask_b32_e64 v247, v137, v247, s[52:53]
	ds_add_u32 v247, v135
	v_xor_b32_e32 v240, s57, v72
	v_cmp_lt_u32_e64 s[52:53], v240, s86
	v_lshrrev_b32_e32 v241, s87, v240
	v_lshl_add_u32 v241, v241, 2, v136
	v_cndmask_b32_e64 v241, v137, v241, s[52:53]
	ds_add_u32 v241, v135
	v_xor_b32_e32 v242, s57, v73
	v_cmp_lt_u32_e64 s[52:53], v242, s86
	v_lshrrev_b32_e32 v243, s87, v242
	v_lshl_add_u32 v243, v243, 2, v136
	v_cndmask_b32_e64 v243, v137, v243, s[52:53]
	ds_add_u32 v243, v135
	v_xor_b32_e32 v244, s57, v74
	v_cmp_lt_u32_e64 s[52:53], v244, s86
	v_lshrrev_b32_e32 v245, s87, v244
	v_lshl_add_u32 v245, v245, 2, v136
	v_cndmask_b32_e64 v245, v137, v245, s[52:53]
	ds_add_u32 v245, v135
	v_xor_b32_e32 v246, s57, v75
	v_cmp_lt_u32_e64 s[52:53], v246, s86
	v_lshrrev_b32_e32 v247, s87, v246
	v_lshl_add_u32 v247, v247, 2, v136
	v_cndmask_b32_e64 v247, v137, v247, s[52:53]
	ds_add_u32 v247, v135
	v_xor_b32_e32 v240, s57, v76
	v_cmp_lt_u32_e64 s[52:53], v240, s86
	v_lshrrev_b32_e32 v241, s87, v240
	v_lshl_add_u32 v241, v241, 2, v136
	v_cndmask_b32_e64 v241, v137, v241, s[52:53]
	ds_add_u32 v241, v135
	v_xor_b32_e32 v242, s57, v77
	v_cmp_lt_u32_e64 s[52:53], v242, s86
	v_lshrrev_b32_e32 v243, s87, v242
	v_lshl_add_u32 v243, v243, 2, v136
	v_cndmask_b32_e64 v243, v137, v243, s[52:53]
	ds_add_u32 v243, v135
	v_xor_b32_e32 v244, s57, v78
	v_cmp_lt_u32_e64 s[52:53], v244, s86
	v_lshrrev_b32_e32 v245, s87, v244
	v_lshl_add_u32 v245, v245, 2, v136
	v_cndmask_b32_e64 v245, v137, v245, s[52:53]
	ds_add_u32 v245, v135
	v_xor_b32_e32 v246, s57, v79
	v_cmp_lt_u32_e64 s[52:53], v246, s86
	v_lshrrev_b32_e32 v247, s87, v246
	v_lshl_add_u32 v247, v247, 2, v136
	v_cndmask_b32_e64 v247, v137, v247, s[52:53]
	ds_add_u32 v247, v135
	s_cmpk_le_u32 s34, 80
	s_cbranch_scc1 .Lsel_hist_done
	v_xor_b32_e32 v240, s57, v80
	v_cmp_lt_u32_e64 s[52:53], v240, s86
	v_lshrrev_b32_e32 v241, s87, v240
	v_lshl_add_u32 v241, v241, 2, v136
	v_cndmask_b32_e64 v241, v137, v241, s[52:53]
	ds_add_u32 v241, v135
	v_xor_b32_e32 v242, s57, v81
	v_cmp_lt_u32_e64 s[52:53], v242, s86
	v_lshrrev_b32_e32 v243, s87, v242
	v_lshl_add_u32 v243, v243, 2, v136
	v_cndmask_b32_e64 v243, v137, v243, s[52:53]
	ds_add_u32 v243, v135
	v_xor_b32_e32 v244, s57, v82
	v_cmp_lt_u32_e64 s[52:53], v244, s86
	v_lshrrev_b32_e32 v245, s87, v244
	v_lshl_add_u32 v245, v245, 2, v136
	v_cndmask_b32_e64 v245, v137, v245, s[52:53]
	ds_add_u32 v245, v135
	v_xor_b32_e32 v246, s57, v83
	v_cmp_lt_u32_e64 s[52:53], v246, s86
	v_lshrrev_b32_e32 v247, s87, v246
	v_lshl_add_u32 v247, v247, 2, v136
	v_cndmask_b32_e64 v247, v137, v247, s[52:53]
	ds_add_u32 v247, v135
	v_xor_b32_e32 v240, s57, v84
	v_cmp_lt_u32_e64 s[52:53], v240, s86
	v_lshrrev_b32_e32 v241, s87, v240
	v_lshl_add_u32 v241, v241, 2, v136
	v_cndmask_b32_e64 v241, v137, v241, s[52:53]
	ds_add_u32 v241, v135
	v_xor_b32_e32 v242, s57, v85
	v_cmp_lt_u32_e64 s[52:53], v242, s86
	v_lshrrev_b32_e32 v243, s87, v242
	v_lshl_add_u32 v243, v243, 2, v136
	v_cndmask_b32_e64 v243, v137, v243, s[52:53]
	ds_add_u32 v243, v135
	v_xor_b32_e32 v244, s57, v86
	v_cmp_lt_u32_e64 s[52:53], v244, s86
	v_lshrrev_b32_e32 v245, s87, v244
	v_lshl_add_u32 v245, v245, 2, v136
	v_cndmask_b32_e64 v245, v137, v245, s[52:53]
	ds_add_u32 v245, v135
	v_xor_b32_e32 v246, s57, v87
	v_cmp_lt_u32_e64 s[52:53], v246, s86
	v_lshrrev_b32_e32 v247, s87, v246
	v_lshl_add_u32 v247, v247, 2, v136
	v_cndmask_b32_e64 v247, v137, v247, s[52:53]
	ds_add_u32 v247, v135
	v_xor_b32_e32 v240, s57, v88
	v_cmp_lt_u32_e64 s[52:53], v240, s86
	v_lshrrev_b32_e32 v241, s87, v240
	v_lshl_add_u32 v241, v241, 2, v136
	v_cndmask_b32_e64 v241, v137, v241, s[52:53]
	ds_add_u32 v241, v135
	v_xor_b32_e32 v242, s57, v89
	v_cmp_lt_u32_e64 s[52:53], v242, s86
	v_lshrrev_b32_e32 v243, s87, v242
	v_lshl_add_u32 v243, v243, 2, v136
	v_cndmask_b32_e64 v243, v137, v243, s[52:53]
	ds_add_u32 v243, v135
	v_xor_b32_e32 v244, s57, v90
	v_cmp_lt_u32_e64 s[52:53], v244, s86
	v_lshrrev_b32_e32 v245, s87, v244
	v_lshl_add_u32 v245, v245, 2, v136
	v_cndmask_b32_e64 v245, v137, v245, s[52:53]
	ds_add_u32 v245, v135
	v_xor_b32_e32 v246, s57, v91
	v_cmp_lt_u32_e64 s[52:53], v246, s86
	v_lshrrev_b32_e32 v247, s87, v246
	v_lshl_add_u32 v247, v247, 2, v136
	v_cndmask_b32_e64 v247, v137, v247, s[52:53]
	ds_add_u32 v247, v135
	v_xor_b32_e32 v240, s57, v92
	v_cmp_lt_u32_e64 s[52:53], v240, s86
	v_lshrrev_b32_e32 v241, s87, v240
	v_lshl_add_u32 v241, v241, 2, v136
	v_cndmask_b32_e64 v241, v137, v241, s[52:53]
	ds_add_u32 v241, v135
	v_xor_b32_e32 v242, s57, v93
	v_cmp_lt_u32_e64 s[52:53], v242, s86
	v_lshrrev_b32_e32 v243, s87, v242
	v_lshl_add_u32 v243, v243, 2, v136
	v_cndmask_b32_e64 v243, v137, v243, s[52:53]
	ds_add_u32 v243, v135
	v_xor_b32_e32 v244, s57, v94
	v_cmp_lt_u32_e64 s[52:53], v244, s86
	v_lshrrev_b32_e32 v245, s87, v244
	v_lshl_add_u32 v245, v245, 2, v136
	v_cndmask_b32_e64 v245, v137, v245, s[52:53]
	ds_add_u32 v245, v135
	v_xor_b32_e32 v246, s57, v95
	v_cmp_lt_u32_e64 s[52:53], v246, s86
	v_lshrrev_b32_e32 v247, s87, v246
	v_lshl_add_u32 v247, v247, 2, v136
	v_cndmask_b32_e64 v247, v137, v247, s[52:53]
	ds_add_u32 v247, v135
	s_cmpk_le_u32 s34, 96
	s_cbranch_scc1 .Lsel_hist_done
	v_xor_b32_e32 v240, s57, v208
	v_cmp_lt_u32_e64 s[52:53], v240, s86
	v_lshrrev_b32_e32 v241, s87, v240
	v_lshl_add_u32 v241, v241, 2, v136
	v_cndmask_b32_e64 v241, v137, v241, s[52:53]
	ds_add_u32 v241, v135
	v_xor_b32_e32 v242, s57, v209
	v_cmp_lt_u32_e64 s[52:53], v242, s86
	v_lshrrev_b32_e32 v243, s87, v242
	v_lshl_add_u32 v243, v243, 2, v136
	v_cndmask_b32_e64 v243, v137, v243, s[52:53]
	ds_add_u32 v243, v135
	v_xor_b32_e32 v244, s57, v210
	v_cmp_lt_u32_e64 s[52:53], v244, s86
	v_lshrrev_b32_e32 v245, s87, v244
	v_lshl_add_u32 v245, v245, 2, v136
	v_cndmask_b32_e64 v245, v137, v245, s[52:53]
	ds_add_u32 v245, v135
	v_xor_b32_e32 v246, s57, v211
	v_cmp_lt_u32_e64 s[52:53], v246, s86
	v_lshrrev_b32_e32 v247, s87, v246
	v_lshl_add_u32 v247, v247, 2, v136
	v_cndmask_b32_e64 v247, v137, v247, s[52:53]
	ds_add_u32 v247, v135
	v_xor_b32_e32 v240, s57, v212
	v_cmp_lt_u32_e64 s[52:53], v240, s86
	v_lshrrev_b32_e32 v241, s87, v240
	v_lshl_add_u32 v241, v241, 2, v136
	v_cndmask_b32_e64 v241, v137, v241, s[52:53]
	ds_add_u32 v241, v135
	v_xor_b32_e32 v242, s57, v213
	v_cmp_lt_u32_e64 s[52:53], v242, s86
	v_lshrrev_b32_e32 v243, s87, v242
	v_lshl_add_u32 v243, v243, 2, v136
	v_cndmask_b32_e64 v243, v137, v243, s[52:53]
	ds_add_u32 v243, v135
	v_xor_b32_e32 v244, s57, v214
	v_cmp_lt_u32_e64 s[52:53], v244, s86
	v_lshrrev_b32_e32 v245, s87, v244
	v_lshl_add_u32 v245, v245, 2, v136
	v_cndmask_b32_e64 v245, v137, v245, s[52:53]
	ds_add_u32 v245, v135
	v_xor_b32_e32 v246, s57, v215
	v_cmp_lt_u32_e64 s[52:53], v246, s86
	v_lshrrev_b32_e32 v247, s87, v246
	v_lshl_add_u32 v247, v247, 2, v136
	v_cndmask_b32_e64 v247, v137, v247, s[52:53]
	ds_add_u32 v247, v135
	v_xor_b32_e32 v240, s57, v216
	v_cmp_lt_u32_e64 s[52:53], v240, s86
	v_lshrrev_b32_e32 v241, s87, v240
	v_lshl_add_u32 v241, v241, 2, v136
	v_cndmask_b32_e64 v241, v137, v241, s[52:53]
	ds_add_u32 v241, v135
	v_xor_b32_e32 v242, s57, v217
	v_cmp_lt_u32_e64 s[52:53], v242, s86
	v_lshrrev_b32_e32 v243, s87, v242
	v_lshl_add_u32 v243, v243, 2, v136
	v_cndmask_b32_e64 v243, v137, v243, s[52:53]
	ds_add_u32 v243, v135
	v_xor_b32_e32 v244, s57, v218
	v_cmp_lt_u32_e64 s[52:53], v244, s86
	v_lshrrev_b32_e32 v245, s87, v244
	v_lshl_add_u32 v245, v245, 2, v136
	v_cndmask_b32_e64 v245, v137, v245, s[52:53]
	ds_add_u32 v245, v135
	v_xor_b32_e32 v246, s57, v219
	v_cmp_lt_u32_e64 s[52:53], v246, s86
	v_lshrrev_b32_e32 v247, s87, v246
	v_lshl_add_u32 v247, v247, 2, v136
	v_cndmask_b32_e64 v247, v137, v247, s[52:53]
	ds_add_u32 v247, v135
	v_xor_b32_e32 v240, s57, v220
	v_cmp_lt_u32_e64 s[52:53], v240, s86
	v_lshrrev_b32_e32 v241, s87, v240
	v_lshl_add_u32 v241, v241, 2, v136
	v_cndmask_b32_e64 v241, v137, v241, s[52:53]
	ds_add_u32 v241, v135
	v_xor_b32_e32 v242, s57, v221
	v_cmp_lt_u32_e64 s[52:53], v242, s86
	v_lshrrev_b32_e32 v243, s87, v242
	v_lshl_add_u32 v243, v243, 2, v136
	v_cndmask_b32_e64 v243, v137, v243, s[52:53]
	ds_add_u32 v243, v135
	v_xor_b32_e32 v244, s57, v222
	v_cmp_lt_u32_e64 s[52:53], v244, s86
	v_lshrrev_b32_e32 v245, s87, v244
	v_lshl_add_u32 v245, v245, 2, v136
	v_cndmask_b32_e64 v245, v137, v245, s[52:53]
	ds_add_u32 v245, v135
	v_xor_b32_e32 v246, s57, v223
	v_cmp_lt_u32_e64 s[52:53], v246, s86
	v_lshrrev_b32_e32 v247, s87, v246
	v_lshl_add_u32 v247, v247, 2, v136
	v_cndmask_b32_e64 v247, v137, v247, s[52:53]
	ds_add_u32 v247, v135
	s_cmpk_le_u32 s34, 112
	s_cbranch_scc1 .Lsel_hist_done
	v_xor_b32_e32 v240, s57, v224
	v_cmp_lt_u32_e64 s[52:53], v240, s86
	v_lshrrev_b32_e32 v241, s87, v240
	v_lshl_add_u32 v241, v241, 2, v136
	v_cndmask_b32_e64 v241, v137, v241, s[52:53]
	ds_add_u32 v241, v135
	v_xor_b32_e32 v242, s57, v225
	v_cmp_lt_u32_e64 s[52:53], v242, s86
	v_lshrrev_b32_e32 v243, s87, v242
	v_lshl_add_u32 v243, v243, 2, v136
	v_cndmask_b32_e64 v243, v137, v243, s[52:53]
	ds_add_u32 v243, v135
	v_xor_b32_e32 v244, s57, v226
	v_cmp_lt_u32_e64 s[52:53], v244, s86
	v_lshrrev_b32_e32 v245, s87, v244
	v_lshl_add_u32 v245, v245, 2, v136
	v_cndmask_b32_e64 v245, v137, v245, s[52:53]
	ds_add_u32 v245, v135
	v_xor_b32_e32 v246, s57, v227
	v_cmp_lt_u32_e64 s[52:53], v246, s86
	v_lshrrev_b32_e32 v247, s87, v246
	v_lshl_add_u32 v247, v247, 2, v136
	v_cndmask_b32_e64 v247, v137, v247, s[52:53]
	ds_add_u32 v247, v135
	v_xor_b32_e32 v240, s57, v228
	v_cmp_lt_u32_e64 s[52:53], v240, s86
	v_lshrrev_b32_e32 v241, s87, v240
	v_lshl_add_u32 v241, v241, 2, v136
	v_cndmask_b32_e64 v241, v137, v241, s[52:53]
	ds_add_u32 v241, v135
	v_xor_b32_e32 v242, s57, v229
	v_cmp_lt_u32_e64 s[52:53], v242, s86
	v_lshrrev_b32_e32 v243, s87, v242
	v_lshl_add_u32 v243, v243, 2, v136
	v_cndmask_b32_e64 v243, v137, v243, s[52:53]
	ds_add_u32 v243, v135
	v_xor_b32_e32 v244, s57, v230
	v_cmp_lt_u32_e64 s[52:53], v244, s86
	v_lshrrev_b32_e32 v245, s87, v244
	v_lshl_add_u32 v245, v245, 2, v136
	v_cndmask_b32_e64 v245, v137, v245, s[52:53]
	ds_add_u32 v245, v135
	v_xor_b32_e32 v246, s57, v231
	v_cmp_lt_u32_e64 s[52:53], v246, s86
	v_lshrrev_b32_e32 v247, s87, v246
	v_lshl_add_u32 v247, v247, 2, v136
	v_cndmask_b32_e64 v247, v137, v247, s[52:53]
	ds_add_u32 v247, v135
	v_xor_b32_e32 v240, s57, v232
	v_cmp_lt_u32_e64 s[52:53], v240, s86
	v_lshrrev_b32_e32 v241, s87, v240
	v_lshl_add_u32 v241, v241, 2, v136
	v_cndmask_b32_e64 v241, v137, v241, s[52:53]
	ds_add_u32 v241, v135
	v_xor_b32_e32 v242, s57, v233
	v_cmp_lt_u32_e64 s[52:53], v242, s86
	v_lshrrev_b32_e32 v243, s87, v242
	v_lshl_add_u32 v243, v243, 2, v136
	v_cndmask_b32_e64 v243, v137, v243, s[52:53]
	ds_add_u32 v243, v135
	v_xor_b32_e32 v244, s57, v234
	v_cmp_lt_u32_e64 s[52:53], v244, s86
	v_lshrrev_b32_e32 v245, s87, v244
	v_lshl_add_u32 v245, v245, 2, v136
	v_cndmask_b32_e64 v245, v137, v245, s[52:53]
	ds_add_u32 v245, v135
	v_xor_b32_e32 v246, s57, v235
	v_cmp_lt_u32_e64 s[52:53], v246, s86
	v_lshrrev_b32_e32 v247, s87, v246
	v_lshl_add_u32 v247, v247, 2, v136
	v_cndmask_b32_e64 v247, v137, v247, s[52:53]
	ds_add_u32 v247, v135
	v_xor_b32_e32 v240, s57, v236
	v_cmp_lt_u32_e64 s[52:53], v240, s86
	v_lshrrev_b32_e32 v241, s87, v240
	v_lshl_add_u32 v241, v241, 2, v136
	v_cndmask_b32_e64 v241, v137, v241, s[52:53]
	ds_add_u32 v241, v135
	v_xor_b32_e32 v242, s57, v237
	v_cmp_lt_u32_e64 s[52:53], v242, s86
	v_lshrrev_b32_e32 v243, s87, v242
	v_lshl_add_u32 v243, v243, 2, v136
	v_cndmask_b32_e64 v243, v137, v243, s[52:53]
	ds_add_u32 v243, v135
	v_xor_b32_e32 v244, s57, v238
	v_cmp_lt_u32_e64 s[52:53], v244, s86
	v_lshrrev_b32_e32 v245, s87, v244
	v_lshl_add_u32 v245, v245, 2, v136
	v_cndmask_b32_e64 v245, v137, v245, s[52:53]
	ds_add_u32 v245, v135
	v_xor_b32_e32 v246, s57, v239
	v_cmp_lt_u32_e64 s[52:53], v246, s86
	v_lshrrev_b32_e32 v247, s87, v246
	v_lshl_add_u32 v247, v247, 2, v136
	v_cndmask_b32_e64 v247, v137, v247, s[52:53]
	ds_add_u32 v247, v135
.Lsel_hist_done:
	s_waitcnt lgkmcnt(0)
	v_lshl_add_u32 v140, v131, 7, v136
	v_mov_b32_e32 v141, 0
	ds_read_b128 v[240:243], v140 offset:0
	ds_read_b128 v[244:247], v140 offset:16
	s_waitcnt lgkmcnt(0)
	v_add3_u32 v141, v141, v240, v241
	v_add3_u32 v141, v141, v242, v243
	v_add3_u32 v141, v141, v244, v245
	v_add3_u32 v141, v141, v246, v247
	ds_read_b128 v[240:243], v140 offset:32
	ds_read_b128 v[244:247], v140 offset:48
	s_waitcnt lgkmcnt(0)
	v_add3_u32 v141, v141, v240, v241
	v_add3_u32 v141, v141, v242, v243
	v_add3_u32 v141, v141, v244, v245
	v_add3_u32 v141, v141, v246, v247
	ds_read_b128 v[240:243], v140 offset:64
	ds_read_b128 v[244:247], v140 offset:80
	s_waitcnt lgkmcnt(0)
	v_add3_u32 v141, v141, v240, v241
	v_add3_u32 v141, v141, v242, v243
	v_add3_u32 v141, v141, v244, v245
	v_add3_u32 v141, v141, v246, v247
	ds_read_b128 v[240:243], v140 offset:96
	ds_read_b128 v[244:247], v140 offset:112
	s_waitcnt lgkmcnt(0)
	v_add3_u32 v141, v141, v240, v241
	v_add3_u32 v141, v141, v242, v243
	v_add3_u32 v141, v141, v244, v245
	v_add3_u32 v141, v141, v246, v247
	v_mov_b32_e32 v142, v141
	v_subrev_u32_e32 v240, 1, v131
	v_cmp_le_u32_e64 s[52:53], 1, v131
	v_and_b32_e32 v240, 63, v240
	v_lshlrev_b32_e32 v240, 2, v240
	ds_bpermute_b32 v241, v240, v142
	s_waitcnt lgkmcnt(0)
	v_cndmask_b32_e64 v241, 0, v241, s[52:53]
	v_add_u32_e32 v142, v142, v241
	v_subrev_u32_e32 v240, 2, v131
	v_cmp_le_u32_e64 s[52:53], 2, v131
	v_and_b32_e32 v240, 63, v240
	v_lshlrev_b32_e32 v240, 2, v240
	ds_bpermute_b32 v241, v240, v142
	s_waitcnt lgkmcnt(0)
	v_cndmask_b32_e64 v241, 0, v241, s[52:53]
	v_add_u32_e32 v142, v142, v241
	v_subrev_u32_e32 v240, 4, v131
	v_cmp_le_u32_e64 s[52:53], 4, v131
	v_and_b32_e32 v240, 63, v240
	v_lshlrev_b32_e32 v240, 2, v240
	ds_bpermute_b32 v241, v240, v142
	s_waitcnt lgkmcnt(0)
	v_cndmask_b32_e64 v241, 0, v241, s[52:53]
	v_add_u32_e32 v142, v142, v241
	v_subrev_u32_e32 v240, 8, v131
	v_cmp_le_u32_e64 s[52:53], 8, v131
	v_and_b32_e32 v240, 63, v240
	v_lshlrev_b32_e32 v240, 2, v240
	ds_bpermute_b32 v241, v240, v142
	s_waitcnt lgkmcnt(0)
	v_cndmask_b32_e64 v241, 0, v241, s[52:53]
	v_add_u32_e32 v142, v142, v241
	v_subrev_u32_e32 v240, 16, v131
	v_cmp_le_u32_e64 s[52:53], 16, v131
	v_and_b32_e32 v240, 63, v240
	v_lshlrev_b32_e32 v240, 2, v240
	ds_bpermute_b32 v241, v240, v142
	s_waitcnt lgkmcnt(0)
	v_cndmask_b32_e64 v241, 0, v241, s[52:53]
	v_add_u32_e32 v142, v142, v241
	v_subrev_u32_e32 v240, 32, v131
	v_cmp_le_u32_e64 s[52:53], 32, v131
	v_and_b32_e32 v240, 63, v240
	v_lshlrev_b32_e32 v240, 2, v240
	ds_bpermute_b32 v241, v240, v142
	s_waitcnt lgkmcnt(0)
	v_cndmask_b32_e64 v241, 0, v241, s[52:53]
	v_add_u32_e32 v142, v142, v241
	v_sub_u32_e32 v242, v142, v141
	v_cmp_gt_u32_e64 s[52:53], s56, v242
	v_cmp_le_u32_e64 s[54:55], s56, v142
	s_nop 1
	s_and_b64 s[52:53], s[52:53], s[54:55]
	s_ff1_i32_b64 s89, s[52:53]
	s_nop 3
	v_readlane_b32 s93, v242, s89
	s_sub_u32 s56, s56, s93
	s_lshl_b32 s93, s89, 7
	v_add3_u32 v140, v136, s93, v133
	ds_read_b32 v143, v140
	s_mov_b32 s90, 0
	s_waitcnt lgkmcnt(0)
	v_readlane_b32 s91, v143, 0
	s_add_u32 s90, s90, s91
	s_cmp_ge_u32 s90, s56
	s_cbranch_scc1 .Lsel_f0
	v_readlane_b32 s91, v143, 1
	s_add_u32 s90, s90, s91
	s_cmp_ge_u32 s90, s56
	s_cbranch_scc1 .Lsel_f1
	v_readlane_b32 s91, v143, 2
	s_add_u32 s90, s90, s91
	s_cmp_ge_u32 s90, s56
	s_cbranch_scc1 .Lsel_f2
	v_readlane_b32 s91, v143, 3
	s_add_u32 s90, s90, s91
	s_cmp_ge_u32 s90, s56
	s_cbranch_scc1 .Lsel_f3
	v_readlane_b32 s91, v143, 4
	s_add_u32 s90, s90, s91
	s_cmp_ge_u32 s90, s56
	s_cbranch_scc1 .Lsel_f4
	v_readlane_b32 s91, v143, 5
	s_add_u32 s90, s90, s91
	s_cmp_ge_u32 s90, s56
	s_cbranch_scc1 .Lsel_f5
	v_readlane_b32 s91, v143, 6
	s_add_u32 s90, s90, s91
	s_cmp_ge_u32 s90, s56
	s_cbranch_scc1 .Lsel_f6
	v_readlane_b32 s91, v143, 7
	s_add_u32 s90, s90, s91
	s_cmp_ge_u32 s90, s56
	s_cbranch_scc1 .Lsel_f7
	v_readlane_b32 s91, v143, 8
	s_add_u32 s90, s90, s91
	s_cmp_ge_u32 s90, s56
	s_cbranch_scc1 .Lsel_f8
	v_readlane_b32 s91, v143, 9
	s_add_u32 s90, s90, s91
	s_cmp_ge_u32 s90, s56
	s_cbranch_scc1 .Lsel_f9
	v_readlane_b32 s91, v143, 10
	s_add_u32 s90, s90, s91
	s_cmp_ge_u32 s90, s56
	s_cbranch_scc1 .Lsel_f10
	v_readlane_b32 s91, v143, 11
	s_add_u32 s90, s90, s91
	s_cmp_ge_u32 s90, s56
	s_cbranch_scc1 .Lsel_f11
	v_readlane_b32 s91, v143, 12
	s_add_u32 s90, s90, s91
	s_cmp_ge_u32 s90, s56
	s_cbranch_scc1 .Lsel_f12
	v_readlane_b32 s91, v143, 13
	s_add_u32 s90, s90, s91
	s_cmp_ge_u32 s90, s56
	s_cbranch_scc1 .Lsel_f13
	v_readlane_b32 s91, v143, 14
	s_add_u32 s90, s90, s91
	s_cmp_ge_u32 s90, s56
	s_cbranch_scc1 .Lsel_f14
	v_readlane_b32 s91, v143, 15
	s_add_u32 s90, s90, s91
	s_cmp_ge_u32 s90, s56
	s_cbranch_scc1 .Lsel_f15
	v_readlane_b32 s91, v143, 16
	s_add_u32 s90, s90, s91
	s_cmp_ge_u32 s90, s56
	s_cbranch_scc1 .Lsel_f16
	v_readlane_b32 s91, v143, 17
	s_add_u32 s90, s90, s91
	s_cmp_ge_u32 s90, s56
	s_cbranch_scc1 .Lsel_f17
	v_readlane_b32 s91, v143, 18
	s_add_u32 s90, s90, s91
	s_cmp_ge_u32 s90, s56
	s_cbranch_scc1 .Lsel_f18
	v_readlane_b32 s91, v143, 19
	s_add_u32 s90, s90, s91
	s_cmp_ge_u32 s90, s56
	s_cbranch_scc1 .Lsel_f19
	v_readlane_b32 s91, v143, 20
	s_add_u32 s90, s90, s91
	s_cmp_ge_u32 s90, s56
	s_cbranch_scc1 .Lsel_f20
	v_readlane_b32 s91, v143, 21
	s_add_u32 s90, s90, s91
	s_cmp_ge_u32 s90, s56
	s_cbranch_scc1 .Lsel_f21
	v_readlane_b32 s91, v143, 22
	s_add_u32 s90, s90, s91
	s_cmp_ge_u32 s90, s56
	s_cbranch_scc1 .Lsel_f22
	v_readlane_b32 s91, v143, 23
	s_add_u32 s90, s90, s91
	s_cmp_ge_u32 s90, s56
	s_cbranch_scc1 .Lsel_f23
	v_readlane_b32 s91, v143, 24
	s_add_u32 s90, s90, s91
	s_cmp_ge_u32 s90, s56
	s_cbranch_scc1 .Lsel_f24
	v_readlane_b32 s91, v143, 25
	s_add_u32 s90, s90, s91
	s_cmp_ge_u32 s90, s56
	s_cbranch_scc1 .Lsel_f25
	v_readlane_b32 s91, v143, 26
	s_add_u32 s90, s90, s91
	s_cmp_ge_u32 s90, s56
	s_cbranch_scc1 .Lsel_f26
	v_readlane_b32 s91, v143, 27
	s_add_u32 s90, s90, s91
	s_cmp_ge_u32 s90, s56
	s_cbranch_scc1 .Lsel_f27
	v_readlane_b32 s91, v143, 28
	s_add_u32 s90, s90, s91
	s_cmp_ge_u32 s90, s56
	s_cbranch_scc1 .Lsel_f28
	v_readlane_b32 s91, v143, 29
	s_add_u32 s90, s90, s91
	s_cmp_ge_u32 s90, s56
	s_cbranch_scc1 .Lsel_f29
	v_readlane_b32 s91, v143, 30
	s_add_u32 s90, s90, s91
	s_cmp_ge_u32 s90, s56
	s_cbranch_scc1 .Lsel_f30
	v_readlane_b32 s91, v143, 31
	s_add_u32 s90, s90, s91
	s_cmp_ge_u32 s90, s56
	s_cbranch_scc1 .Lsel_f31
.Lsel_f31:
	s_movk_i32 s92, 31
	s_branch .Lsel_found
.Lsel_f30:
	s_movk_i32 s92, 30
	s_branch .Lsel_found
.Lsel_f29:
	s_movk_i32 s92, 29
	s_branch .Lsel_found
.Lsel_f28:
	s_movk_i32 s92, 28
	s_branch .Lsel_found
.Lsel_f27:
	s_movk_i32 s92, 27
	s_branch .Lsel_found
.Lsel_f26:
	s_movk_i32 s92, 26
	s_branch .Lsel_found
.Lsel_f25:
	s_movk_i32 s92, 25
	s_branch .Lsel_found
.Lsel_f24:
	s_movk_i32 s92, 24
	s_branch .Lsel_found
.Lsel_f23:
	s_movk_i32 s92, 23
	s_branch .Lsel_found
.Lsel_f22:
	s_movk_i32 s92, 22
	s_branch .Lsel_found
.Lsel_f21:
	s_movk_i32 s92, 21
	s_branch .Lsel_found
.Lsel_f20:
	s_movk_i32 s92, 20
	s_branch .Lsel_found
.Lsel_f19:
	s_movk_i32 s92, 19
	s_branch .Lsel_found
.Lsel_f18:
	s_movk_i32 s92, 18
	s_branch .Lsel_found
.Lsel_f17:
	s_movk_i32 s92, 17
	s_branch .Lsel_found
.Lsel_f16:
	s_movk_i32 s92, 16
	s_branch .Lsel_found
.Lsel_f15:
	s_movk_i32 s92, 15
	s_branch .Lsel_found
.Lsel_f14:
	s_movk_i32 s92, 14
	s_branch .Lsel_found
.Lsel_f13:
	s_movk_i32 s92, 13
	s_branch .Lsel_found
.Lsel_f12:
	s_movk_i32 s92, 12
	s_branch .Lsel_found
.Lsel_f11:
	s_movk_i32 s92, 11
	s_branch .Lsel_found
.Lsel_f10:
	s_movk_i32 s92, 10
	s_branch .Lsel_found
.Lsel_f9:
	s_movk_i32 s92, 9
	s_branch .Lsel_found
.Lsel_f8:
	s_movk_i32 s92, 8
	s_branch .Lsel_found
.Lsel_f7:
	s_movk_i32 s92, 7
	s_branch .Lsel_found
.Lsel_f6:
	s_movk_i32 s92, 6
	s_branch .Lsel_found
.Lsel_f5:
	s_movk_i32 s92, 5
	s_branch .Lsel_found
.Lsel_f4:
	s_movk_i32 s92, 4
	s_branch .Lsel_found
.Lsel_f3:
	s_movk_i32 s92, 3
	s_branch .Lsel_found
.Lsel_f2:
	s_movk_i32 s92, 2
	s_branch .Lsel_found
.Lsel_f1:
	s_movk_i32 s92, 1
	s_branch .Lsel_found
.Lsel_f0:
	s_movk_i32 s92, 0
.Lsel_found:
	s_sub_u32 s90, s90, s91
	s_sub_u32 s56, s56, s90
	s_lshl_b32 s93, s89, 5
	s_or_b32 s93, s93, s92
	s_lshl_b32 s93, s93, s87
	s_or_b32 s57, s57, s93
	s_cmp_eq_u32 s88, 0
	s_cbranch_scc0 .Lsel_np1
	s_mov_b32 s86, 0x200000
	s_mov_b32 s87, 10
	s_mov_b32 s88, 1
	s_branch .Lsel_pass
.Lsel_np1:
	s_cmp_eq_u32 s88, 1
	s_cbranch_scc0 .Lsel_final
	s_movk_i32 s86, 0x400
	s_mov_b32 s87, 0
	s_mov_b32 s88, 2
	s_branch .Lsel_pass
.Lsel_final:
	v_mov_b32_e32 v240, 0
	v_mov_b32_e32 v241, 0
	v_mov_b32_e32 v242, 0
	v_mov_b32_e32 v243, 0
	v_cmp_lt_u32_e64 s[96:97], v0, s57
	v_cmp_eq_u32_e64 s[54:55], v0, s57
	v_cmp_lt_u32_e64 s[98:99], v1, s57
	v_cmp_eq_u32_e64 s[52:53], v1, s57
	s_nop 0
	v_writelane_b32 v250, s96, 0
	v_writelane_b32 v251, s97, 0
	v_writelane_b32 v240, s54, 0
	v_writelane_b32 v241, s55, 0
	v_writelane_b32 v250, s98, 1
	v_writelane_b32 v251, s99, 1
	v_writelane_b32 v240, s52, 1
	v_writelane_b32 v241, s53, 1
	v_cmp_lt_u32_e64 s[96:97], v2, s57
	v_cmp_eq_u32_e64 s[54:55], v2, s57
	v_cmp_lt_u32_e64 s[98:99], v3, s57
	v_cmp_eq_u32_e64 s[52:53], v3, s57
	s_nop 0
	v_writelane_b32 v250, s96, 2
	v_writelane_b32 v251, s97, 2
	v_writelane_b32 v240, s54, 2
	v_writelane_b32 v241, s55, 2
	v_writelane_b32 v250, s98, 3
	v_writelane_b32 v251, s99, 3
	v_writelane_b32 v240, s52, 3
	v_writelane_b32 v241, s53, 3
	v_cmp_lt_u32_e64 s[96:97], v4, s57
	v_cmp_eq_u32_e64 s[54:55], v4, s57
	v_cmp_lt_u32_e64 s[98:99], v5, s57
	v_cmp_eq_u32_e64 s[52:53], v5, s57
	s_nop 0
	v_writelane_b32 v250, s96, 4
	v_writelane_b32 v251, s97, 4
	v_writelane_b32 v240, s54, 4
	v_writelane_b32 v241, s55, 4
	v_writelane_b32 v250, s98, 5
	v_writelane_b32 v251, s99, 5
	v_writelane_b32 v240, s52, 5
	v_writelane_b32 v241, s53, 5
	v_cmp_lt_u32_e64 s[96:97], v6, s57
	v_cmp_eq_u32_e64 s[54:55], v6, s57
	v_cmp_lt_u32_e64 s[98:99], v7, s57
	v_cmp_eq_u32_e64 s[52:53], v7, s57
	s_nop 0
	v_writelane_b32 v250, s96, 6
	v_writelane_b32 v251, s97, 6
	v_writelane_b32 v240, s54, 6
	v_writelane_b32 v241, s55, 6
	v_writelane_b32 v250, s98, 7
	v_writelane_b32 v251, s99, 7
	v_writelane_b32 v240, s52, 7
	v_writelane_b32 v241, s53, 7
	v_cmp_lt_u32_e64 s[96:97], v8, s57
	v_cmp_eq_u32_e64 s[54:55], v8, s57
	v_cmp_lt_u32_e64 s[98:99], v9, s57
	v_cmp_eq_u32_e64 s[52:53], v9, s57
	s_nop 0
	v_writelane_b32 v250, s96, 8
	v_writelane_b32 v251, s97, 8
	v_writelane_b32 v240, s54, 8
	v_writelane_b32 v241, s55, 8
	v_writelane_b32 v250, s98, 9
	v_writelane_b32 v251, s99, 9
	v_writelane_b32 v240, s52, 9
	v_writelane_b32 v241, s53, 9
	v_cmp_lt_u32_e64 s[96:97], v10, s57
	v_cmp_eq_u32_e64 s[54:55], v10, s57
	v_cmp_lt_u32_e64 s[98:99], v11, s57
	v_cmp_eq_u32_e64 s[52:53], v11, s57
	s_nop 0
	v_writelane_b32 v250, s96, 10
	v_writelane_b32 v251, s97, 10
	v_writelane_b32 v240, s54, 10
	v_writelane_b32 v241, s55, 10
	v_writelane_b32 v250, s98, 11
	v_writelane_b32 v251, s99, 11
	v_writelane_b32 v240, s52, 11
	v_writelane_b32 v241, s53, 11
	v_cmp_lt_u32_e64 s[96:97], v12, s57
	v_cmp_eq_u32_e64 s[54:55], v12, s57
	v_cmp_lt_u32_e64 s[98:99], v13, s57
	v_cmp_eq_u32_e64 s[52:53], v13, s57
	s_nop 0
	v_writelane_b32 v250, s96, 12
	v_writelane_b32 v251, s97, 12
	v_writelane_b32 v240, s54, 12
	v_writelane_b32 v241, s55, 12
	v_writelane_b32 v250, s98, 13
	v_writelane_b32 v251, s99, 13
	v_writelane_b32 v240, s52, 13
	v_writelane_b32 v241, s53, 13
	v_cmp_lt_u32_e64 s[96:97], v14, s57
	v_cmp_eq_u32_e64 s[54:55], v14, s57
	v_cmp_lt_u32_e64 s[98:99], v15, s57
	v_cmp_eq_u32_e64 s[52:53], v15, s57
	s_nop 0
	v_writelane_b32 v250, s96, 14
	v_writelane_b32 v251, s97, 14
	v_writelane_b32 v240, s54, 14
	v_writelane_b32 v241, s55, 14
	v_writelane_b32 v250, s98, 15
	v_writelane_b32 v251, s99, 15
	v_writelane_b32 v240, s52, 15
	v_writelane_b32 v241, s53, 15
	s_cmpk_le_u32 s34, 16
	s_cbranch_scc1 .Lsel_ties
	v_cmp_lt_u32_e64 s[96:97], v16, s57
	v_cmp_eq_u32_e64 s[54:55], v16, s57
	v_cmp_lt_u32_e64 s[98:99], v17, s57
	v_cmp_eq_u32_e64 s[52:53], v17, s57
	s_nop 0
	v_writelane_b32 v250, s96, 16
	v_writelane_b32 v251, s97, 16
	v_writelane_b32 v240, s54, 16
	v_writelane_b32 v241, s55, 16
	v_writelane_b32 v250, s98, 17
	v_writelane_b32 v251, s99, 17
	v_writelane_b32 v240, s52, 17
	v_writelane_b32 v241, s53, 17
	v_cmp_lt_u32_e64 s[96:97], v18, s57
	v_cmp_eq_u32_e64 s[54:55], v18, s57
	v_cmp_lt_u32_e64 s[98:99], v19, s57
	v_cmp_eq_u32_e64 s[52:53], v19, s57
	s_nop 0
	v_writelane_b32 v250, s96, 18
	v_writelane_b32 v251, s97, 18
	v_writelane_b32 v240, s54, 18
	v_writelane_b32 v241, s55, 18
	v_writelane_b32 v250, s98, 19
	v_writelane_b32 v251, s99, 19
	v_writelane_b32 v240, s52, 19
	v_writelane_b32 v241, s53, 19
	v_cmp_lt_u32_e64 s[96:97], v20, s57
	v_cmp_eq_u32_e64 s[54:55], v20, s57
	v_cmp_lt_u32_e64 s[98:99], v21, s57
	v_cmp_eq_u32_e64 s[52:53], v21, s57
	s_nop 0
	v_writelane_b32 v250, s96, 20
	v_writelane_b32 v251, s97, 20
	v_writelane_b32 v240, s54, 20
	v_writelane_b32 v241, s55, 20
	v_writelane_b32 v250, s98, 21
	v_writelane_b32 v251, s99, 21
	v_writelane_b32 v240, s52, 21
	v_writelane_b32 v241, s53, 21
	v_cmp_lt_u32_e64 s[96:97], v22, s57
	v_cmp_eq_u32_e64 s[54:55], v22, s57
	v_cmp_lt_u32_e64 s[98:99], v23, s57
	v_cmp_eq_u32_e64 s[52:53], v23, s57
	s_nop 0
	v_writelane_b32 v250, s96, 22
	v_writelane_b32 v251, s97, 22
	v_writelane_b32 v240, s54, 22
	v_writelane_b32 v241, s55, 22
	v_writelane_b32 v250, s98, 23
	v_writelane_b32 v251, s99, 23
	v_writelane_b32 v240, s52, 23
	v_writelane_b32 v241, s53, 23
	v_cmp_lt_u32_e64 s[96:97], v24, s57
	v_cmp_eq_u32_e64 s[54:55], v24, s57
	v_cmp_lt_u32_e64 s[98:99], v25, s57
	v_cmp_eq_u32_e64 s[52:53], v25, s57
	s_nop 0
	v_writelane_b32 v250, s96, 24
	v_writelane_b32 v251, s97, 24
	v_writelane_b32 v240, s54, 24
	v_writelane_b32 v241, s55, 24
	v_writelane_b32 v250, s98, 25
	v_writelane_b32 v251, s99, 25
	v_writelane_b32 v240, s52, 25
	v_writelane_b32 v241, s53, 25
	v_cmp_lt_u32_e64 s[96:97], v26, s57
	v_cmp_eq_u32_e64 s[54:55], v26, s57
	v_cmp_lt_u32_e64 s[98:99], v27, s57
	v_cmp_eq_u32_e64 s[52:53], v27, s57
	s_nop 0
	v_writelane_b32 v250, s96, 26
	v_writelane_b32 v251, s97, 26
	v_writelane_b32 v240, s54, 26
	v_writelane_b32 v241, s55, 26
	v_writelane_b32 v250, s98, 27
	v_writelane_b32 v251, s99, 27
	v_writelane_b32 v240, s52, 27
	v_writelane_b32 v241, s53, 27
	v_cmp_lt_u32_e64 s[96:97], v28, s57
	v_cmp_eq_u32_e64 s[54:55], v28, s57
	v_cmp_lt_u32_e64 s[98:99], v29, s57
	v_cmp_eq_u32_e64 s[52:53], v29, s57
	s_nop 0
	v_writelane_b32 v250, s96, 28
	v_writelane_b32 v251, s97, 28
	v_writelane_b32 v240, s54, 28
	v_writelane_b32 v241, s55, 28
	v_writelane_b32 v250, s98, 29
	v_writelane_b32 v251, s99, 29
	v_writelane_b32 v240, s52, 29
	v_writelane_b32 v241, s53, 29
	v_cmp_lt_u32_e64 s[96:97], v30, s57
	v_cmp_eq_u32_e64 s[54:55], v30, s57
	v_cmp_lt_u32_e64 s[98:99], v31, s57
	v_cmp_eq_u32_e64 s[52:53], v31, s57
	s_nop 0
	v_writelane_b32 v250, s96, 30
	v_writelane_b32 v251, s97, 30
	v_writelane_b32 v240, s54, 30
	v_writelane_b32 v241, s55, 30
	v_writelane_b32 v250, s98, 31
	v_writelane_b32 v251, s99, 31
	v_writelane_b32 v240, s52, 31
	v_writelane_b32 v241, s53, 31
	s_cmpk_le_u32 s34, 32
	s_cbranch_scc1 .Lsel_ties
	v_cmp_lt_u32_e64 s[96:97], v32, s57
	v_cmp_eq_u32_e64 s[54:55], v32, s57
	v_cmp_lt_u32_e64 s[98:99], v33, s57
	v_cmp_eq_u32_e64 s[52:53], v33, s57
	s_nop 0
	v_writelane_b32 v250, s96, 32
	v_writelane_b32 v251, s97, 32
	v_writelane_b32 v240, s54, 32
	v_writelane_b32 v241, s55, 32
	v_writelane_b32 v250, s98, 33
	v_writelane_b32 v251, s99, 33
	v_writelane_b32 v240, s52, 33
	v_writelane_b32 v241, s53, 33
	v_cmp_lt_u32_e64 s[96:97], v34, s57
	v_cmp_eq_u32_e64 s[54:55], v34, s57
	v_cmp_lt_u32_e64 s[98:99], v35, s57
	v_cmp_eq_u32_e64 s[52:53], v35, s57
	s_nop 0
	v_writelane_b32 v250, s96, 34
	v_writelane_b32 v251, s97, 34
	v_writelane_b32 v240, s54, 34
	v_writelane_b32 v241, s55, 34
	v_writelane_b32 v250, s98, 35
	v_writelane_b32 v251, s99, 35
	v_writelane_b32 v240, s52, 35
	v_writelane_b32 v241, s53, 35
	v_cmp_lt_u32_e64 s[96:97], v36, s57
	v_cmp_eq_u32_e64 s[54:55], v36, s57
	v_cmp_lt_u32_e64 s[98:99], v37, s57
	v_cmp_eq_u32_e64 s[52:53], v37, s57
	s_nop 0
	v_writelane_b32 v250, s96, 36
	v_writelane_b32 v251, s97, 36
	v_writelane_b32 v240, s54, 36
	v_writelane_b32 v241, s55, 36
	v_writelane_b32 v250, s98, 37
	v_writelane_b32 v251, s99, 37
	v_writelane_b32 v240, s52, 37
	v_writelane_b32 v241, s53, 37
	v_cmp_lt_u32_e64 s[96:97], v38, s57
	v_cmp_eq_u32_e64 s[54:55], v38, s57
	v_cmp_lt_u32_e64 s[98:99], v39, s57
	v_cmp_eq_u32_e64 s[52:53], v39, s57
	s_nop 0
	v_writelane_b32 v250, s96, 38
	v_writelane_b32 v251, s97, 38
	v_writelane_b32 v240, s54, 38
	v_writelane_b32 v241, s55, 38
	v_writelane_b32 v250, s98, 39
	v_writelane_b32 v251, s99, 39
	v_writelane_b32 v240, s52, 39
	v_writelane_b32 v241, s53, 39
	v_cmp_lt_u32_e64 s[96:97], v40, s57
	v_cmp_eq_u32_e64 s[54:55], v40, s57
	v_cmp_lt_u32_e64 s[98:99], v41, s57
	v_cmp_eq_u32_e64 s[52:53], v41, s57
	s_nop 0
	v_writelane_b32 v250, s96, 40
	v_writelane_b32 v251, s97, 40
	v_writelane_b32 v240, s54, 40
	v_writelane_b32 v241, s55, 40
	v_writelane_b32 v250, s98, 41
	v_writelane_b32 v251, s99, 41
	v_writelane_b32 v240, s52, 41
	v_writelane_b32 v241, s53, 41
	v_cmp_lt_u32_e64 s[96:97], v42, s57
	v_cmp_eq_u32_e64 s[54:55], v42, s57
	v_cmp_lt_u32_e64 s[98:99], v43, s57
	v_cmp_eq_u32_e64 s[52:53], v43, s57
	s_nop 0
	v_writelane_b32 v250, s96, 42
	v_writelane_b32 v251, s97, 42
	v_writelane_b32 v240, s54, 42
	v_writelane_b32 v241, s55, 42
	v_writelane_b32 v250, s98, 43
	v_writelane_b32 v251, s99, 43
	v_writelane_b32 v240, s52, 43
	v_writelane_b32 v241, s53, 43
	v_cmp_lt_u32_e64 s[96:97], v44, s57
	v_cmp_eq_u32_e64 s[54:55], v44, s57
	v_cmp_lt_u32_e64 s[98:99], v45, s57
	v_cmp_eq_u32_e64 s[52:53], v45, s57
	s_nop 0
	v_writelane_b32 v250, s96, 44
	v_writelane_b32 v251, s97, 44
	v_writelane_b32 v240, s54, 44
	v_writelane_b32 v241, s55, 44
	v_writelane_b32 v250, s98, 45
	v_writelane_b32 v251, s99, 45
	v_writelane_b32 v240, s52, 45
	v_writelane_b32 v241, s53, 45
	v_cmp_lt_u32_e64 s[96:97], v46, s57
	v_cmp_eq_u32_e64 s[54:55], v46, s57
	v_cmp_lt_u32_e64 s[98:99], v47, s57
	v_cmp_eq_u32_e64 s[52:53], v47, s57
	s_nop 0
	v_writelane_b32 v250, s96, 46
	v_writelane_b32 v251, s97, 46
	v_writelane_b32 v240, s54, 46
	v_writelane_b32 v241, s55, 46
	v_writelane_b32 v250, s98, 47
	v_writelane_b32 v251, s99, 47
	v_writelane_b32 v240, s52, 47
	v_writelane_b32 v241, s53, 47
	s_cmpk_le_u32 s34, 48
	s_cbranch_scc1 .Lsel_ties
	v_cmp_lt_u32_e64 s[96:97], v48, s57
	v_cmp_eq_u32_e64 s[54:55], v48, s57
	v_cmp_lt_u32_e64 s[98:99], v49, s57
	v_cmp_eq_u32_e64 s[52:53], v49, s57
	s_nop 0
	v_writelane_b32 v250, s96, 48
	v_writelane_b32 v251, s97, 48
	v_writelane_b32 v240, s54, 48
	v_writelane_b32 v241, s55, 48
	v_writelane_b32 v250, s98, 49
	v_writelane_b32 v251, s99, 49
	v_writelane_b32 v240, s52, 49
	v_writelane_b32 v241, s53, 49
	v_cmp_lt_u32_e64 s[96:97], v50, s57
	v_cmp_eq_u32_e64 s[54:55], v50, s57
	v_cmp_lt_u32_e64 s[98:99], v51, s57
	v_cmp_eq_u32_e64 s[52:53], v51, s57
	s_nop 0
	v_writelane_b32 v250, s96, 50
	v_writelane_b32 v251, s97, 50
	v_writelane_b32 v240, s54, 50
	v_writelane_b32 v241, s55, 50
	v_writelane_b32 v250, s98, 51
	v_writelane_b32 v251, s99, 51
	v_writelane_b32 v240, s52, 51
	v_writelane_b32 v241, s53, 51
	v_cmp_lt_u32_e64 s[96:97], v52, s57
	v_cmp_eq_u32_e64 s[54:55], v52, s57
	v_cmp_lt_u32_e64 s[98:99], v53, s57
	v_cmp_eq_u32_e64 s[52:53], v53, s57
	s_nop 0
	v_writelane_b32 v250, s96, 52
	v_writelane_b32 v251, s97, 52
	v_writelane_b32 v240, s54, 52
	v_writelane_b32 v241, s55, 52
	v_writelane_b32 v250, s98, 53
	v_writelane_b32 v251, s99, 53
	v_writelane_b32 v240, s52, 53
	v_writelane_b32 v241, s53, 53
	v_cmp_lt_u32_e64 s[96:97], v54, s57
	v_cmp_eq_u32_e64 s[54:55], v54, s57
	v_cmp_lt_u32_e64 s[98:99], v55, s57
	v_cmp_eq_u32_e64 s[52:53], v55, s57
	s_nop 0
	v_writelane_b32 v250, s96, 54
	v_writelane_b32 v251, s97, 54
	v_writelane_b32 v240, s54, 54
	v_writelane_b32 v241, s55, 54
	v_writelane_b32 v250, s98, 55
	v_writelane_b32 v251, s99, 55
	v_writelane_b32 v240, s52, 55
	v_writelane_b32 v241, s53, 55
	v_cmp_lt_u32_e64 s[96:97], v56, s57
	v_cmp_eq_u32_e64 s[54:55], v56, s57
	v_cmp_lt_u32_e64 s[98:99], v57, s57
	v_cmp_eq_u32_e64 s[52:53], v57, s57
	s_nop 0
	v_writelane_b32 v250, s96, 56
	v_writelane_b32 v251, s97, 56
	v_writelane_b32 v240, s54, 56
	v_writelane_b32 v241, s55, 56
	v_writelane_b32 v250, s98, 57
	v_writelane_b32 v251, s99, 57
	v_writelane_b32 v240, s52, 57
	v_writelane_b32 v241, s53, 57
	v_cmp_lt_u32_e64 s[96:97], v58, s57
	v_cmp_eq_u32_e64 s[54:55], v58, s57
	v_cmp_lt_u32_e64 s[98:99], v59, s57
	v_cmp_eq_u32_e64 s[52:53], v59, s57
	s_nop 0
	v_writelane_b32 v250, s96, 58
	v_writelane_b32 v251, s97, 58
	v_writelane_b32 v240, s54, 58
	v_writelane_b32 v241, s55, 58
	v_writelane_b32 v250, s98, 59
	v_writelane_b32 v251, s99, 59
	v_writelane_b32 v240, s52, 59
	v_writelane_b32 v241, s53, 59
	v_cmp_lt_u32_e64 s[96:97], v60, s57
	v_cmp_eq_u32_e64 s[54:55], v60, s57
	v_cmp_lt_u32_e64 s[98:99], v61, s57
	v_cmp_eq_u32_e64 s[52:53], v61, s57
	s_nop 0
	v_writelane_b32 v250, s96, 60
	v_writelane_b32 v251, s97, 60
	v_writelane_b32 v240, s54, 60
	v_writelane_b32 v241, s55, 60
	v_writelane_b32 v250, s98, 61
	v_writelane_b32 v251, s99, 61
	v_writelane_b32 v240, s52, 61
	v_writelane_b32 v241, s53, 61
	v_cmp_lt_u32_e64 s[96:97], v62, s57
	v_cmp_eq_u32_e64 s[54:55], v62, s57
	v_cmp_lt_u32_e64 s[98:99], v63, s57
	v_cmp_eq_u32_e64 s[52:53], v63, s57
	s_nop 0
	v_writelane_b32 v250, s96, 62
	v_writelane_b32 v251, s97, 62
	v_writelane_b32 v240, s54, 62
	v_writelane_b32 v241, s55, 62
	v_writelane_b32 v250, s98, 63
	v_writelane_b32 v251, s99, 63
	v_writelane_b32 v240, s52, 63
	v_writelane_b32 v241, s53, 63
	s_cmpk_le_u32 s34, 64
	s_cbranch_scc1 .Lsel_ties
	v_cmp_lt_u32_e64 s[96:97], v64, s57
	v_cmp_eq_u32_e64 s[54:55], v64, s57
	v_cmp_lt_u32_e64 s[98:99], v65, s57
	v_cmp_eq_u32_e64 s[52:53], v65, s57
	s_nop 0
	v_writelane_b32 v252, s96, 0
	v_writelane_b32 v253, s97, 0
	v_writelane_b32 v242, s54, 0
	v_writelane_b32 v243, s55, 0
	v_writelane_b32 v252, s98, 1
	v_writelane_b32 v253, s99, 1
	v_writelane_b32 v242, s52, 1
	v_writelane_b32 v243, s53, 1
	v_cmp_lt_u32_e64 s[96:97], v66, s57
	v_cmp_eq_u32_e64 s[54:55], v66, s57
	v_cmp_lt_u32_e64 s[98:99], v67, s57
	v_cmp_eq_u32_e64 s[52:53], v67, s57
	s_nop 0
	v_writelane_b32 v252, s96, 2
	v_writelane_b32 v253, s97, 2
	v_writelane_b32 v242, s54, 2
	v_writelane_b32 v243, s55, 2
	v_writelane_b32 v252, s98, 3
	v_writelane_b32 v253, s99, 3
	v_writelane_b32 v242, s52, 3
	v_writelane_b32 v243, s53, 3
	v_cmp_lt_u32_e64 s[96:97], v68, s57
	v_cmp_eq_u32_e64 s[54:55], v68, s57
	v_cmp_lt_u32_e64 s[98:99], v69, s57
	v_cmp_eq_u32_e64 s[52:53], v69, s57
	s_nop 0
	v_writelane_b32 v252, s96, 4
	v_writelane_b32 v253, s97, 4
	v_writelane_b32 v242, s54, 4
	v_writelane_b32 v243, s55, 4
	v_writelane_b32 v252, s98, 5
	v_writelane_b32 v253, s99, 5
	v_writelane_b32 v242, s52, 5
	v_writelane_b32 v243, s53, 5
	v_cmp_lt_u32_e64 s[96:97], v70, s57
	v_cmp_eq_u32_e64 s[54:55], v70, s57
	v_cmp_lt_u32_e64 s[98:99], v71, s57
	v_cmp_eq_u32_e64 s[52:53], v71, s57
	s_nop 0
	v_writelane_b32 v252, s96, 6
	v_writelane_b32 v253, s97, 6
	v_writelane_b32 v242, s54, 6
	v_writelane_b32 v243, s55, 6
	v_writelane_b32 v252, s98, 7
	v_writelane_b32 v253, s99, 7
	v_writelane_b32 v242, s52, 7
	v_writelane_b32 v243, s53, 7
	v_cmp_lt_u32_e64 s[96:97], v72, s57
	v_cmp_eq_u32_e64 s[54:55], v72, s57
	v_cmp_lt_u32_e64 s[98:99], v73, s57
	v_cmp_eq_u32_e64 s[52:53], v73, s57
	s_nop 0
	v_writelane_b32 v252, s96, 8
	v_writelane_b32 v253, s97, 8
	v_writelane_b32 v242, s54, 8
	v_writelane_b32 v243, s55, 8
	v_writelane_b32 v252, s98, 9
	v_writelane_b32 v253, s99, 9
	v_writelane_b32 v242, s52, 9
	v_writelane_b32 v243, s53, 9
	v_cmp_lt_u32_e64 s[96:97], v74, s57
	v_cmp_eq_u32_e64 s[54:55], v74, s57
	v_cmp_lt_u32_e64 s[98:99], v75, s57
	v_cmp_eq_u32_e64 s[52:53], v75, s57
	s_nop 0
	v_writelane_b32 v252, s96, 10
	v_writelane_b32 v253, s97, 10
	v_writelane_b32 v242, s54, 10
	v_writelane_b32 v243, s55, 10
	v_writelane_b32 v252, s98, 11
	v_writelane_b32 v253, s99, 11
	v_writelane_b32 v242, s52, 11
	v_writelane_b32 v243, s53, 11
	v_cmp_lt_u32_e64 s[96:97], v76, s57
	v_cmp_eq_u32_e64 s[54:55], v76, s57
	v_cmp_lt_u32_e64 s[98:99], v77, s57
	v_cmp_eq_u32_e64 s[52:53], v77, s57
	s_nop 0
	v_writelane_b32 v252, s96, 12
	v_writelane_b32 v253, s97, 12
	v_writelane_b32 v242, s54, 12
	v_writelane_b32 v243, s55, 12
	v_writelane_b32 v252, s98, 13
	v_writelane_b32 v253, s99, 13
	v_writelane_b32 v242, s52, 13
	v_writelane_b32 v243, s53, 13
	v_cmp_lt_u32_e64 s[96:97], v78, s57
	v_cmp_eq_u32_e64 s[54:55], v78, s57
	v_cmp_lt_u32_e64 s[98:99], v79, s57
	v_cmp_eq_u32_e64 s[52:53], v79, s57
	s_nop 0
	v_writelane_b32 v252, s96, 14
	v_writelane_b32 v253, s97, 14
	v_writelane_b32 v242, s54, 14
	v_writelane_b32 v243, s55, 14
	v_writelane_b32 v252, s98, 15
	v_writelane_b32 v253, s99, 15
	v_writelane_b32 v242, s52, 15
	v_writelane_b32 v243, s53, 15
	s_cmpk_le_u32 s34, 80
	s_cbranch_scc1 .Lsel_ties
	v_cmp_lt_u32_e64 s[96:97], v80, s57
	v_cmp_eq_u32_e64 s[54:55], v80, s57
	v_cmp_lt_u32_e64 s[98:99], v81, s57
	v_cmp_eq_u32_e64 s[52:53], v81, s57
	s_nop 0
	v_writelane_b32 v252, s96, 16
	v_writelane_b32 v253, s97, 16
	v_writelane_b32 v242, s54, 16
	v_writelane_b32 v243, s55, 16
	v_writelane_b32 v252, s98, 17
	v_writelane_b32 v253, s99, 17
	v_writelane_b32 v242, s52, 17
	v_writelane_b32 v243, s53, 17
	v_cmp_lt_u32_e64 s[96:97], v82, s57
	v_cmp_eq_u32_e64 s[54:55], v82, s57
	v_cmp_lt_u32_e64 s[98:99], v83, s57
	v_cmp_eq_u32_e64 s[52:53], v83, s57
	s_nop 0
	v_writelane_b32 v252, s96, 18
	v_writelane_b32 v253, s97, 18
	v_writelane_b32 v242, s54, 18
	v_writelane_b32 v243, s55, 18
	v_writelane_b32 v252, s98, 19
	v_writelane_b32 v253, s99, 19
	v_writelane_b32 v242, s52, 19
	v_writelane_b32 v243, s53, 19
	v_cmp_lt_u32_e64 s[96:97], v84, s57
	v_cmp_eq_u32_e64 s[54:55], v84, s57
	v_cmp_lt_u32_e64 s[98:99], v85, s57
	v_cmp_eq_u32_e64 s[52:53], v85, s57
	s_nop 0
	v_writelane_b32 v252, s96, 20
	v_writelane_b32 v253, s97, 20
	v_writelane_b32 v242, s54, 20
	v_writelane_b32 v243, s55, 20
	v_writelane_b32 v252, s98, 21
	v_writelane_b32 v253, s99, 21
	v_writelane_b32 v242, s52, 21
	v_writelane_b32 v243, s53, 21
	v_cmp_lt_u32_e64 s[96:97], v86, s57
	v_cmp_eq_u32_e64 s[54:55], v86, s57
	v_cmp_lt_u32_e64 s[98:99], v87, s57
	v_cmp_eq_u32_e64 s[52:53], v87, s57
	s_nop 0
	v_writelane_b32 v252, s96, 22
	v_writelane_b32 v253, s97, 22
	v_writelane_b32 v242, s54, 22
	v_writelane_b32 v243, s55, 22
	v_writelane_b32 v252, s98, 23
	v_writelane_b32 v253, s99, 23
	v_writelane_b32 v242, s52, 23
	v_writelane_b32 v243, s53, 23
	v_cmp_lt_u32_e64 s[96:97], v88, s57
	v_cmp_eq_u32_e64 s[54:55], v88, s57
	v_cmp_lt_u32_e64 s[98:99], v89, s57
	v_cmp_eq_u32_e64 s[52:53], v89, s57
	s_nop 0
	v_writelane_b32 v252, s96, 24
	v_writelane_b32 v253, s97, 24
	v_writelane_b32 v242, s54, 24
	v_writelane_b32 v243, s55, 24
	v_writelane_b32 v252, s98, 25
	v_writelane_b32 v253, s99, 25
	v_writelane_b32 v242, s52, 25
	v_writelane_b32 v243, s53, 25
	v_cmp_lt_u32_e64 s[96:97], v90, s57
	v_cmp_eq_u32_e64 s[54:55], v90, s57
	v_cmp_lt_u32_e64 s[98:99], v91, s57
	v_cmp_eq_u32_e64 s[52:53], v91, s57
	s_nop 0
	v_writelane_b32 v252, s96, 26
	v_writelane_b32 v253, s97, 26
	v_writelane_b32 v242, s54, 26
	v_writelane_b32 v243, s55, 26
	v_writelane_b32 v252, s98, 27
	v_writelane_b32 v253, s99, 27
	v_writelane_b32 v242, s52, 27
	v_writelane_b32 v243, s53, 27
	v_cmp_lt_u32_e64 s[96:97], v92, s57
	v_cmp_eq_u32_e64 s[54:55], v92, s57
	v_cmp_lt_u32_e64 s[98:99], v93, s57
	v_cmp_eq_u32_e64 s[52:53], v93, s57
	s_nop 0
	v_writelane_b32 v252, s96, 28
	v_writelane_b32 v253, s97, 28
	v_writelane_b32 v242, s54, 28
	v_writelane_b32 v243, s55, 28
	v_writelane_b32 v252, s98, 29
	v_writelane_b32 v253, s99, 29
	v_writelane_b32 v242, s52, 29
	v_writelane_b32 v243, s53, 29
	v_cmp_lt_u32_e64 s[96:97], v94, s57
	v_cmp_eq_u32_e64 s[54:55], v94, s57
	v_cmp_lt_u32_e64 s[98:99], v95, s57
	v_cmp_eq_u32_e64 s[52:53], v95, s57
	s_nop 0
	v_writelane_b32 v252, s96, 30
	v_writelane_b32 v253, s97, 30
	v_writelane_b32 v242, s54, 30
	v_writelane_b32 v243, s55, 30
	v_writelane_b32 v252, s98, 31
	v_writelane_b32 v253, s99, 31
	v_writelane_b32 v242, s52, 31
	v_writelane_b32 v243, s53, 31
	s_cmpk_le_u32 s34, 96
	s_cbranch_scc1 .Lsel_ties
	v_cmp_lt_u32_e64 s[96:97], v208, s57
	v_cmp_eq_u32_e64 s[54:55], v208, s57
	v_cmp_lt_u32_e64 s[98:99], v209, s57
	v_cmp_eq_u32_e64 s[52:53], v209, s57
	s_nop 0
	v_writelane_b32 v252, s96, 32
	v_writelane_b32 v253, s97, 32
	v_writelane_b32 v242, s54, 32
	v_writelane_b32 v243, s55, 32
	v_writelane_b32 v252, s98, 33
	v_writelane_b32 v253, s99, 33
	v_writelane_b32 v242, s52, 33
	v_writelane_b32 v243, s53, 33
	v_cmp_lt_u32_e64 s[96:97], v210, s57
	v_cmp_eq_u32_e64 s[54:55], v210, s57
	v_cmp_lt_u32_e64 s[98:99], v211, s57
	v_cmp_eq_u32_e64 s[52:53], v211, s57
	s_nop 0
	v_writelane_b32 v252, s96, 34
	v_writelane_b32 v253, s97, 34
	v_writelane_b32 v242, s54, 34
	v_writelane_b32 v243, s55, 34
	v_writelane_b32 v252, s98, 35
	v_writelane_b32 v253, s99, 35
	v_writelane_b32 v242, s52, 35
	v_writelane_b32 v243, s53, 35
	v_cmp_lt_u32_e64 s[96:97], v212, s57
	v_cmp_eq_u32_e64 s[54:55], v212, s57
	v_cmp_lt_u32_e64 s[98:99], v213, s57
	v_cmp_eq_u32_e64 s[52:53], v213, s57
	s_nop 0
	v_writelane_b32 v252, s96, 36
	v_writelane_b32 v253, s97, 36
	v_writelane_b32 v242, s54, 36
	v_writelane_b32 v243, s55, 36
	v_writelane_b32 v252, s98, 37
	v_writelane_b32 v253, s99, 37
	v_writelane_b32 v242, s52, 37
	v_writelane_b32 v243, s53, 37
	v_cmp_lt_u32_e64 s[96:97], v214, s57
	v_cmp_eq_u32_e64 s[54:55], v214, s57
	v_cmp_lt_u32_e64 s[98:99], v215, s57
	v_cmp_eq_u32_e64 s[52:53], v215, s57
	s_nop 0
	v_writelane_b32 v252, s96, 38
	v_writelane_b32 v253, s97, 38
	v_writelane_b32 v242, s54, 38
	v_writelane_b32 v243, s55, 38
	v_writelane_b32 v252, s98, 39
	v_writelane_b32 v253, s99, 39
	v_writelane_b32 v242, s52, 39
	v_writelane_b32 v243, s53, 39
	v_cmp_lt_u32_e64 s[96:97], v216, s57
	v_cmp_eq_u32_e64 s[54:55], v216, s57
	v_cmp_lt_u32_e64 s[98:99], v217, s57
	v_cmp_eq_u32_e64 s[52:53], v217, s57
	s_nop 0
	v_writelane_b32 v252, s96, 40
	v_writelane_b32 v253, s97, 40
	v_writelane_b32 v242, s54, 40
	v_writelane_b32 v243, s55, 40
	v_writelane_b32 v252, s98, 41
	v_writelane_b32 v253, s99, 41
	v_writelane_b32 v242, s52, 41
	v_writelane_b32 v243, s53, 41
	v_cmp_lt_u32_e64 s[96:97], v218, s57
	v_cmp_eq_u32_e64 s[54:55], v218, s57
	v_cmp_lt_u32_e64 s[98:99], v219, s57
	v_cmp_eq_u32_e64 s[52:53], v219, s57
	s_nop 0
	v_writelane_b32 v252, s96, 42
	v_writelane_b32 v253, s97, 42
	v_writelane_b32 v242, s54, 42
	v_writelane_b32 v243, s55, 42
	v_writelane_b32 v252, s98, 43
	v_writelane_b32 v253, s99, 43
	v_writelane_b32 v242, s52, 43
	v_writelane_b32 v243, s53, 43
	v_cmp_lt_u32_e64 s[96:97], v220, s57
	v_cmp_eq_u32_e64 s[54:55], v220, s57
	v_cmp_lt_u32_e64 s[98:99], v221, s57
	v_cmp_eq_u32_e64 s[52:53], v221, s57
	s_nop 0
	v_writelane_b32 v252, s96, 44
	v_writelane_b32 v253, s97, 44
	v_writelane_b32 v242, s54, 44
	v_writelane_b32 v243, s55, 44
	v_writelane_b32 v252, s98, 45
	v_writelane_b32 v253, s99, 45
	v_writelane_b32 v242, s52, 45
	v_writelane_b32 v243, s53, 45
	v_cmp_lt_u32_e64 s[96:97], v222, s57
	v_cmp_eq_u32_e64 s[54:55], v222, s57
	v_cmp_lt_u32_e64 s[98:99], v223, s57
	v_cmp_eq_u32_e64 s[52:53], v223, s57
	s_nop 0
	v_writelane_b32 v252, s96, 46
	v_writelane_b32 v253, s97, 46
	v_writelane_b32 v242, s54, 46
	v_writelane_b32 v243, s55, 46
	v_writelane_b32 v252, s98, 47
	v_writelane_b32 v253, s99, 47
	v_writelane_b32 v242, s52, 47
	v_writelane_b32 v243, s53, 47
	s_cmpk_le_u32 s34, 112
	s_cbranch_scc1 .Lsel_ties
	v_cmp_lt_u32_e64 s[96:97], v224, s57
	v_cmp_eq_u32_e64 s[54:55], v224, s57
	v_cmp_lt_u32_e64 s[98:99], v225, s57
	v_cmp_eq_u32_e64 s[52:53], v225, s57
	s_nop 0
	v_writelane_b32 v252, s96, 48
	v_writelane_b32 v253, s97, 48
	v_writelane_b32 v242, s54, 48
	v_writelane_b32 v243, s55, 48
	v_writelane_b32 v252, s98, 49
	v_writelane_b32 v253, s99, 49
	v_writelane_b32 v242, s52, 49
	v_writelane_b32 v243, s53, 49
	v_cmp_lt_u32_e64 s[96:97], v226, s57
	v_cmp_eq_u32_e64 s[54:55], v226, s57
	v_cmp_lt_u32_e64 s[98:99], v227, s57
	v_cmp_eq_u32_e64 s[52:53], v227, s57
	s_nop 0
	v_writelane_b32 v252, s96, 50
	v_writelane_b32 v253, s97, 50
	v_writelane_b32 v242, s54, 50
	v_writelane_b32 v243, s55, 50
	v_writelane_b32 v252, s98, 51
	v_writelane_b32 v253, s99, 51
	v_writelane_b32 v242, s52, 51
	v_writelane_b32 v243, s53, 51
	v_cmp_lt_u32_e64 s[96:97], v228, s57
	v_cmp_eq_u32_e64 s[54:55], v228, s57
	v_cmp_lt_u32_e64 s[98:99], v229, s57
	v_cmp_eq_u32_e64 s[52:53], v229, s57
	s_nop 0
	v_writelane_b32 v252, s96, 52
	v_writelane_b32 v253, s97, 52
	v_writelane_b32 v242, s54, 52
	v_writelane_b32 v243, s55, 52
	v_writelane_b32 v252, s98, 53
	v_writelane_b32 v253, s99, 53
	v_writelane_b32 v242, s52, 53
	v_writelane_b32 v243, s53, 53
	v_cmp_lt_u32_e64 s[96:97], v230, s57
	v_cmp_eq_u32_e64 s[54:55], v230, s57
	v_cmp_lt_u32_e64 s[98:99], v231, s57
	v_cmp_eq_u32_e64 s[52:53], v231, s57
	s_nop 0
	v_writelane_b32 v252, s96, 54
	v_writelane_b32 v253, s97, 54
	v_writelane_b32 v242, s54, 54
	v_writelane_b32 v243, s55, 54
	v_writelane_b32 v252, s98, 55
	v_writelane_b32 v253, s99, 55
	v_writelane_b32 v242, s52, 55
	v_writelane_b32 v243, s53, 55
	v_cmp_lt_u32_e64 s[96:97], v232, s57
	v_cmp_eq_u32_e64 s[54:55], v232, s57
	v_cmp_lt_u32_e64 s[98:99], v233, s57
	v_cmp_eq_u32_e64 s[52:53], v233, s57
	s_nop 0
	v_writelane_b32 v252, s96, 56
	v_writelane_b32 v253, s97, 56
	v_writelane_b32 v242, s54, 56
	v_writelane_b32 v243, s55, 56
	v_writelane_b32 v252, s98, 57
	v_writelane_b32 v253, s99, 57
	v_writelane_b32 v242, s52, 57
	v_writelane_b32 v243, s53, 57
	v_cmp_lt_u32_e64 s[96:97], v234, s57
	v_cmp_eq_u32_e64 s[54:55], v234, s57
	v_cmp_lt_u32_e64 s[98:99], v235, s57
	v_cmp_eq_u32_e64 s[52:53], v235, s57
	s_nop 0
	v_writelane_b32 v252, s96, 58
	v_writelane_b32 v253, s97, 58
	v_writelane_b32 v242, s54, 58
	v_writelane_b32 v243, s55, 58
	v_writelane_b32 v252, s98, 59
	v_writelane_b32 v253, s99, 59
	v_writelane_b32 v242, s52, 59
	v_writelane_b32 v243, s53, 59
	v_cmp_lt_u32_e64 s[96:97], v236, s57
	v_cmp_eq_u32_e64 s[54:55], v236, s57
	v_cmp_lt_u32_e64 s[98:99], v237, s57
	v_cmp_eq_u32_e64 s[52:53], v237, s57
	s_nop 0
	v_writelane_b32 v252, s96, 60
	v_writelane_b32 v253, s97, 60
	v_writelane_b32 v242, s54, 60
	v_writelane_b32 v243, s55, 60
	v_writelane_b32 v252, s98, 61
	v_writelane_b32 v253, s99, 61
	v_writelane_b32 v242, s52, 61
	v_writelane_b32 v243, s53, 61
	v_cmp_lt_u32_e64 s[96:97], v238, s57
	v_cmp_eq_u32_e64 s[54:55], v238, s57
	v_cmp_lt_u32_e64 s[98:99], v239, s57
	v_cmp_eq_u32_e64 s[52:53], v239, s57
	s_nop 0
	v_writelane_b32 v252, s96, 62
	v_writelane_b32 v253, s97, 62
	v_writelane_b32 v242, s54, 62
	v_writelane_b32 v243, s55, 62
	v_writelane_b32 v252, s98, 63
	v_writelane_b32 v253, s99, 63
	v_writelane_b32 v242, s52, 63
	v_writelane_b32 v243, s53, 63
.Lsel_ties:
	v_or_b32_e32 v244, v240, v241
	v_cmp_ne_u32_e64 s[98:99], 0, v244
	s_nop 1
.Lsel_tl0:
	s_cmp_eq_u64 s[98:99], 0
	s_cbranch_scc1 .Lsel_tdone0
	s_ff1_i32_b64 s92, s[98:99]
	s_bitset0_b64 s[98:99], s92
	s_nop 3
	v_readlane_b32 s54, v240, s92
	v_readlane_b32 s55, v241, s92
	v_readlane_b32 s96, v250, s92
	v_readlane_b32 s97, v251, s92
	s_nop 1
.Lsel_tk0:
	s_cmp_eq_u32 s56, 0
	s_cbranch_scc1 .Lsel_tw0
	s_cmp_eq_u64 s[54:55], 0
	s_cbranch_scc1 .Lsel_tw0
	s_ff1_i32_b64 s93, s[54:55]
	s_bitset1_b64 s[96:97], s93
	s_bitset0_b64 s[54:55], s93
	s_sub_u32 s56, s56, 1
	s_branch .Lsel_tk0
.Lsel_tw0:
	s_lshl_b64 s[52:53], 1, s92
	s_mov_b64 exec, s[52:53]
	v_mov_b32_e32 v250, s96
	v_mov_b32_e32 v251, s97
	s_mov_b64 exec, -1
	s_branch .Lsel_tl0
.Lsel_tdone0:
	v_or_b32_e32 v244, v242, v243
	v_cmp_ne_u32_e64 s[98:99], 0, v244
	s_nop 1
.Lsel_tl1:
	s_cmp_eq_u64 s[98:99], 0
	s_cbranch_scc1 .Lsel_tdone1
	s_ff1_i32_b64 s92, s[98:99]
	s_bitset0_b64 s[98:99], s92
	s_nop 3
	v_readlane_b32 s54, v242, s92
	v_readlane_b32 s55, v243, s92
	v_readlane_b32 s96, v252, s92
	v_readlane_b32 s97, v253, s92
	s_nop 1

.Lsel_tw1:
	s_lshl_b64 s[52:53], 1, s92
	s_mov_b64 exec, s[52:53]
	v_mov_b32_e32 v252, s96
	v_mov_b32_e32 v253, s97
	s_mov_b64 exec, -1
	s_branch .Lsel_tl1
.Lsel_tdone1:
.Lsel_store:
	v_lshlrev_b32_e32 v254, 16, v131
	v_cmp_gt_u32_e64 s[52:53], s35, v131
	s_nop 1
	s_mov_b64 exec, s[52:53]
	global_store_dwordx2 v254, v[250:251], s[50:51]
	s_mov_b64 exec, -1
	s_cmpk_le_u32 s35, 64
	s_cbranch_scc1 .Lsel_next
	v_add_u32_e32 v240, 64, v131
	v_cmp_gt_u32_e64 s[52:53], s35, v240
	s_add_u32 s98, s50, 0x400000
	s_addc_u32 s99, s51, 0
	s_mov_b64 exec, s[52:53]
	global_store_dwordx2 v254, v[252:253], s[98:99]
	s_mov_b64 exec, -1
.Lsel_next:
	s_add_i32 s19, s19, 1
	s_cmp_lt_u32 s19, 2
	s_cbranch_scc1 .Lsel_q
	s_mov_b64 exec, -1
	s_branch .Lsel_done

	.amdhsa_kernel _Z10fwd_kernel6Params
		.amdhsa_group_segment_fixed_size 0
		.amdhsa_private_segment_fixed_size 0
		.amdhsa_kernarg_size 456
		.amdhsa_user_sgpr_count 2
		.amdhsa_user_sgpr_dispatch_ptr 0
		.amdhsa_user_sgpr_queue_ptr 0
		.amdhsa_user_sgpr_kernarg_segment_ptr 1
		.amdhsa_user_sgpr_dispatch_id 0
		.amdhsa_user_sgpr_kernarg_preload_length 0
		.amdhsa_user_sgpr_kernarg_preload_offset 0
		.amdhsa_user_sgpr_private_segment_size 0
		.amdhsa_uses_dynamic_stack 0
		.amdhsa_enable_private_segment 0
		.amdhsa_system_sgpr_workgroup_id_x 1
		.amdhsa_system_sgpr_workgroup_id_y 0
		.amdhsa_system_sgpr_workgroup_id_z 0
		.amdhsa_system_sgpr_workgroup_info 0
		.amdhsa_system_vgpr_workitem_id 2
		.amdhsa_next_free_vgpr 256
		.amdhsa_next_free_sgpr 102
		.amdhsa_accum_offset 256
		.amdhsa_reserve_vcc 1
		.amdhsa_float_round_mode_32 0
		.amdhsa_float_round_mode_16_64 0
		.amdhsa_float_denorm_mode_32 3
		.amdhsa_float_denorm_mode_16_64 3
		.amdhsa_dx10_clamp 1
		.amdhsa_ieee_mode 1
		.amdhsa_fp16_overflow 0
		.amdhsa_tg_split 0
		.amdhsa_exception_fp_ieee_invalid_op 0
		.amdhsa_exception_fp_denorm_src 0
		.amdhsa_exception_fp_ieee_div_zero 0
		.amdhsa_exception_fp_ieee_overflow 0
		.amdhsa_exception_fp_ieee_underflow 0
		.amdhsa_exception_fp_ieee_inexact 0
		.amdhsa_exception_int_div_zero 0
	.end_amdhsa_kernel

amdhsa.kernels:
  - .agpr_count:     0
    .args:
      - .offset:         0
        .size:           200
        .value_kind:     by_value
      - .offset:         200
        .size:           4
        .value_kind:     hidden_block_count_x
      - .offset:         204
        .size:           4
        .value_kind:     hidden_block_count_y
      - .offset:         208
        .size:           4
        .value_kind:     hidden_block_count_z
      - .offset:         212
        .size:           2
        .value_kind:     hidden_group_size_x
      - .offset:         214
        .size:           2
        .value_kind:     hidden_group_size_y
      - .offset:         216
        .size:           2
        .value_kind:     hidden_group_size_z
      - .offset:         218
        .size:           2
        .value_kind:     hidden_remainder_x
      - .offset:         220
        .size:           2
        .value_kind:     hidden_remainder_y
      - .offset:         222
        .size:           2
        .value_kind:     hidden_remainder_z
      - .offset:         240
        .size:           8
        .value_kind:     hidden_global_offset_x
      - .offset:         248
        .size:           8
        .value_kind:     hidden_global_offset_y
      - .offset:         256
        .size:           8
        .value_kind:     hidden_global_offset_z
      - .offset:         264
        .size:           2
        .value_kind:     hidden_grid_dims
      - .offset:         288
        .size:           8
        .value_kind:     hidden_multigrid_sync_arg
      - .offset:         320
        .size:           4
        .value_kind:     hidden_dynamic_lds_size
    .group_segment_fixed_size: 0
    .kernarg_segment_align: 8
    .kernarg_segment_size: 456
    .language:       OpenCL C
    .language_version:
      - 2
      - 0
    .max_flat_workgroup_size: 512
    .name:           _Z10fwd_kernel6Params
    .private_segment_fixed_size: 0
    .sgpr_count:     108
    .sgpr_spill_count: 19
    .symbol:         _Z10fwd_kernel6Params.kd
    .uniform_work_group_size: 1
    .uses_dynamic_stack: false
    .vgpr_count:     256
    .vgpr_spill_count: 0
    .wavefront_size: 64
